# combo3 + loop-edge: ds_reads first in each load segment, loop-tail counter updates moved before the loop-back barrier
# baseline (speedup 1.0000x reference)
.LBB0_707:
	ds_read_b128 v[164:167], v2 offset:0
	ds_read_b128 v[168:171], v2 offset:1024
	ds_read_b128 v[172:175], v2 offset:2048
	ds_read_b128 v[176:179], v2 offset:3072
	ds_read_b128 v[192:195], v2 offset:16384
	ds_read_b128 v[196:199], v2 offset:17408
	ds_read_b128 v[204:207], v2 offset:18432
	ds_read_b128 v[210:213], v2 offset:19456
	ds_read_b128 v[216:219], v203
	ds_read_b128 v[220:223], v203 offset:1024
	ds_read_b128 v[224:227], v203 offset:2048
	ds_read_b128 v[228:231], v203 offset:3072
	ds_read_b128 v[232:235], v203 offset:4096
	ds_read_b128 v[236:239], v203 offset:5120
	ds_read_b128 v[240:243], v203 offset:6144
	ds_read_b128 v[244:247], v203 offset:7168
	s_add_u32 s34, s50, 0xfff80080
	s_addc_u32 s35, s51, -1
	s_add_i32 s61, 0, 0x10000
	s_cmp_eq_u32 s60, 4
	s_cselect_b32 s55, s23, s35
	s_cselect_b32 s54, s22, s34
	s_cselect_b32 s53, s43, s59
	s_cselect_b32 s52, s42, s21
	s_add_i32 s62, 0, 0x14000
	s_add_i32 m0, s29, 0xc000
	s_nop 0
	global_load_lds_dwordx4 v188, s[50:51]
	s_add_i32 m0, s29, 0xe000
	s_nop 0
	global_load_lds_dwordx4 v190, s[50:51]
	s_waitcnt vmcnt(8) lgkmcnt(0)
	s_barrier
	v_mfma_f32_16x16x32_bf16 v[160:163], v[164:167], v[216:219], v[160:163]
	v_mfma_f32_16x16x32_bf16 v[156:159], v[172:175], v[216:219], v[156:159]
	v_mfma_f32_16x16x32_bf16 v[144:147], v[164:167], v[224:227], v[144:147]
	v_mfma_f32_16x16x32_bf16 v[140:143], v[172:175], v[224:227], v[140:143]
	v_mfma_f32_16x16x32_bf16 v[128:131], v[164:167], v[232:235], v[128:131]
	v_mfma_f32_16x16x32_bf16 v[124:127], v[172:175], v[232:235], v[124:127]
	v_mfma_f32_16x16x32_bf16 v[112:115], v[164:167], v[240:243], v[112:115]
	v_mfma_f32_16x16x32_bf16 v[108:111], v[172:175], v[240:243], v[108:111]
	v_mfma_f32_16x16x32_bf16 v[160:163], v[168:171], v[220:223], v[160:163]
	v_mfma_f32_16x16x32_bf16 v[156:159], v[176:179], v[220:223], v[156:159]
	v_mfma_f32_16x16x32_bf16 v[144:147], v[168:171], v[228:231], v[144:147]
	v_mfma_f32_16x16x32_bf16 v[140:143], v[176:179], v[228:231], v[140:143]
	v_mfma_f32_16x16x32_bf16 v[128:131], v[168:171], v[236:239], v[128:131]
	v_mfma_f32_16x16x32_bf16 v[124:127], v[176:179], v[236:239], v[124:127]
	v_mfma_f32_16x16x32_bf16 v[112:115], v[168:171], v[244:247], v[112:115]
	v_mfma_f32_16x16x32_bf16 v[108:111], v[176:179], v[244:247], v[108:111]
	v_mfma_f32_16x16x32_bf16 v[152:155], v[192:195], v[216:219], v[152:155]
	v_mfma_f32_16x16x32_bf16 v[148:151], v[204:207], v[216:219], v[148:151]
	v_mfma_f32_16x16x32_bf16 v[136:139], v[192:195], v[224:227], v[136:139]
	v_mfma_f32_16x16x32_bf16 v[132:135], v[204:207], v[224:227], v[132:135]
	v_mfma_f32_16x16x32_bf16 v[120:123], v[192:195], v[232:235], v[120:123]
	v_mfma_f32_16x16x32_bf16 v[116:119], v[204:207], v[232:235], v[116:119]
	v_mfma_f32_16x16x32_bf16 v[104:107], v[192:195], v[240:243], v[104:107]
	v_mfma_f32_16x16x32_bf16 v[100:103], v[204:207], v[240:243], v[100:103]
	v_mfma_f32_16x16x32_bf16 v[152:155], v[196:199], v[220:223], v[152:155]
	v_mfma_f32_16x16x32_bf16 v[148:151], v[210:213], v[220:223], v[148:151]
	v_mfma_f32_16x16x32_bf16 v[136:139], v[196:199], v[228:231], v[136:139]
	v_mfma_f32_16x16x32_bf16 v[132:135], v[210:213], v[228:231], v[132:135]
	v_mfma_f32_16x16x32_bf16 v[120:123], v[196:199], v[236:239], v[120:123]
	v_mfma_f32_16x16x32_bf16 v[116:119], v[210:213], v[236:239], v[116:119]
	v_mfma_f32_16x16x32_bf16 v[104:107], v[196:199], v[244:247], v[104:107]
	v_mfma_f32_16x16x32_bf16 v[100:103], v[210:213], v[244:247], v[100:103]
	s_barrier
	ds_read_b128 v[216:219], v203 offset:16384
	ds_read_b128 v[220:223], v203 offset:17408
	ds_read_b128 v[224:227], v203 offset:18432
	ds_read_b128 v[228:231], v203 offset:19456
	ds_read_b128 v[232:235], v203 offset:20480
	ds_read_b128 v[236:239], v203 offset:21504
	ds_read_b128 v[240:243], v203 offset:22528
	ds_read_b128 v[244:247], v203 offset:23552
	s_add_i32 s34, s61, s0
	s_mov_b32 m0, s34
	s_nop 0
	global_load_lds_dwordx4 v180, s[52:53]
	s_add_i32 m0, s34, 0x2000
	s_add_u32 s34, s52, 0x4000
	s_addc_u32 s35, s53, 0
	s_add_i32 s61, s62, s0
	global_load_lds_dwordx4 v184, s[52:53]
	s_mov_b32 m0, s61
	v_lshl_add_u64 v[248:249], s[54:55], 0, v[186:187]
	global_load_lds_dwordx4 v180, s[34:35]
	s_add_i32 m0, s61, 0x2000
	s_nop 0
	global_load_lds_dwordx4 v184, s[34:35]
	v_lshl_add_u64 v[200:201], s[54:55], 0, v[182:183]
	s_mov_b32 m0, s29
	s_nop 0
	global_load_lds_dwordx4 v182, s[54:55]
	s_mov_b32 m0, s45
	s_nop 0
	global_load_lds_dwordx4 v186, s[54:55]
	s_waitcnt vmcnt(8) lgkmcnt(0)
	s_barrier
	v_mfma_f32_16x16x32_bf16 v[96:99], v[164:167], v[216:219], v[96:99]
	v_mfma_f32_16x16x32_bf16 v[92:95], v[172:175], v[216:219], v[92:95]
	v_mfma_f32_16x16x32_bf16 v[84:87], v[164:167], v[224:227], v[84:87]
	v_mfma_f32_16x16x32_bf16 v[76:79], v[172:175], v[224:227], v[76:79]
	v_mfma_f32_16x16x32_bf16 v[68:71], v[164:167], v[232:235], v[68:71]
	v_mfma_f32_16x16x32_bf16 v[60:63], v[172:175], v[232:235], v[60:63]
	v_mfma_f32_16x16x32_bf16 v[52:55], v[164:167], v[240:243], v[52:55]
	v_mfma_f32_16x16x32_bf16 v[44:47], v[172:175], v[240:243], v[44:47]
	v_mfma_f32_16x16x32_bf16 v[96:99], v[168:171], v[220:223], v[96:99]
	v_mfma_f32_16x16x32_bf16 v[92:95], v[176:179], v[220:223], v[92:95]
	v_mfma_f32_16x16x32_bf16 v[84:87], v[168:171], v[228:231], v[84:87]
	v_mfma_f32_16x16x32_bf16 v[76:79], v[176:179], v[228:231], v[76:79]
	v_mfma_f32_16x16x32_bf16 v[68:71], v[168:171], v[236:239], v[68:71]
	v_mfma_f32_16x16x32_bf16 v[60:63], v[176:179], v[236:239], v[60:63]
	v_mfma_f32_16x16x32_bf16 v[52:55], v[168:171], v[244:247], v[52:55]
	v_mfma_f32_16x16x32_bf16 v[44:47], v[176:179], v[244:247], v[44:47]
	v_mfma_f32_16x16x32_bf16 v[88:91], v[192:195], v[216:219], v[88:91]
	v_mfma_f32_16x16x32_bf16 v[80:83], v[204:207], v[216:219], v[80:83]
	v_mfma_f32_16x16x32_bf16 v[72:75], v[192:195], v[224:227], v[72:75]
	v_mfma_f32_16x16x32_bf16 v[64:67], v[204:207], v[224:227], v[64:67]
	v_mfma_f32_16x16x32_bf16 v[56:59], v[192:195], v[232:235], v[56:59]
	v_mfma_f32_16x16x32_bf16 v[48:51], v[204:207], v[232:235], v[48:51]
	v_mfma_f32_16x16x32_bf16 v[40:43], v[192:195], v[240:243], v[40:43]
	v_mfma_f32_16x16x32_bf16 v[36:39], v[204:207], v[240:243], v[36:39]
	v_mfma_f32_16x16x32_bf16 v[88:91], v[196:199], v[220:223], v[88:91]
	v_mfma_f32_16x16x32_bf16 v[80:83], v[210:213], v[220:223], v[80:83]
	v_mfma_f32_16x16x32_bf16 v[72:75], v[196:199], v[228:231], v[72:75]
	v_mfma_f32_16x16x32_bf16 v[64:67], v[210:213], v[228:231], v[64:67]
	v_mfma_f32_16x16x32_bf16 v[56:59], v[196:199], v[236:239], v[56:59]
	v_mfma_f32_16x16x32_bf16 v[48:51], v[210:213], v[236:239], v[48:51]
	v_mfma_f32_16x16x32_bf16 v[40:43], v[196:199], v[244:247], v[40:43]
	v_mfma_f32_16x16x32_bf16 v[36:39], v[210:213], v[244:247], v[36:39]
	s_barrier
	ds_read_b128 v[164:167], v2 offset:32768
	ds_read_b128 v[168:171], v2 offset:33792
	ds_read_b128 v[172:175], v2 offset:34816
	ds_read_b128 v[176:179], v2 offset:35840
	ds_read_b128 v[192:195], v2 offset:49152
	ds_read_b128 v[196:199], v2 offset:50176
	ds_read_b128 v[204:207], v2 offset:51200
	ds_read_b128 v[210:213], v2 offset:52224
	ds_read_b128 v[216:219], v203 offset:32768
	ds_read_b128 v[220:223], v203 offset:33792
	ds_read_b128 v[224:227], v203 offset:34816
	ds_read_b128 v[228:231], v203 offset:35840
	ds_read_b128 v[232:235], v203 offset:36864
	ds_read_b128 v[236:239], v203 offset:37888
	ds_read_b128 v[240:243], v203 offset:38912
	ds_read_b128 v[244:247], v203 offset:39936
	s_add_i32 s61, 0, 0x18000
	s_add_i32 s62, 0, 0x1c000
	s_add_u32 s34, s54, 0x80000
	s_addc_u32 s35, s55, 0
	s_mov_b32 m0, s82
	s_nop 0
	global_load_lds_dwordx4 v182, s[34:35]
	s_mov_b32 m0, s90
	s_nop 0
	global_load_lds_dwordx4 v186, s[34:35]
	s_waitcnt vmcnt(8) lgkmcnt(0)
	s_barrier
	v_mfma_f32_16x16x32_bf16 v[160:163], v[164:167], v[216:219], v[160:163]
	v_mfma_f32_16x16x32_bf16 v[156:159], v[172:175], v[216:219], v[156:159]
	v_mfma_f32_16x16x32_bf16 v[144:147], v[164:167], v[224:227], v[144:147]
	v_mfma_f32_16x16x32_bf16 v[140:143], v[172:175], v[224:227], v[140:143]
	v_mfma_f32_16x16x32_bf16 v[128:131], v[164:167], v[232:235], v[128:131]
	v_mfma_f32_16x16x32_bf16 v[124:127], v[172:175], v[232:235], v[124:127]
	v_mfma_f32_16x16x32_bf16 v[112:115], v[164:167], v[240:243], v[112:115]
	v_mfma_f32_16x16x32_bf16 v[108:111], v[172:175], v[240:243], v[108:111]
	v_mfma_f32_16x16x32_bf16 v[160:163], v[168:171], v[220:223], v[160:163]
	v_mfma_f32_16x16x32_bf16 v[156:159], v[176:179], v[220:223], v[156:159]
	v_mfma_f32_16x16x32_bf16 v[144:147], v[168:171], v[228:231], v[144:147]
	v_mfma_f32_16x16x32_bf16 v[140:143], v[176:179], v[228:231], v[140:143]
	v_mfma_f32_16x16x32_bf16 v[128:131], v[168:171], v[236:239], v[128:131]
	v_mfma_f32_16x16x32_bf16 v[124:127], v[176:179], v[236:239], v[124:127]
	v_mfma_f32_16x16x32_bf16 v[112:115], v[168:171], v[244:247], v[112:115]
	v_mfma_f32_16x16x32_bf16 v[108:111], v[176:179], v[244:247], v[108:111]
	v_mfma_f32_16x16x32_bf16 v[152:155], v[192:195], v[216:219], v[152:155]
	v_mfma_f32_16x16x32_bf16 v[148:151], v[204:207], v[216:219], v[148:151]
	v_mfma_f32_16x16x32_bf16 v[136:139], v[192:195], v[224:227], v[136:139]
	v_mfma_f32_16x16x32_bf16 v[132:135], v[204:207], v[224:227], v[132:135]
	v_mfma_f32_16x16x32_bf16 v[120:123], v[192:195], v[232:235], v[120:123]
	v_mfma_f32_16x16x32_bf16 v[116:119], v[204:207], v[232:235], v[116:119]
	v_mfma_f32_16x16x32_bf16 v[104:107], v[192:195], v[240:243], v[104:107]
	v_mfma_f32_16x16x32_bf16 v[100:103], v[204:207], v[240:243], v[100:103]
	v_mfma_f32_16x16x32_bf16 v[152:155], v[196:199], v[220:223], v[152:155]
	v_mfma_f32_16x16x32_bf16 v[148:151], v[210:213], v[220:223], v[148:151]
	v_mfma_f32_16x16x32_bf16 v[136:139], v[196:199], v[228:231], v[136:139]
	v_mfma_f32_16x16x32_bf16 v[132:135], v[210:213], v[228:231], v[132:135]
	v_mfma_f32_16x16x32_bf16 v[120:123], v[196:199], v[236:239], v[120:123]
	v_mfma_f32_16x16x32_bf16 v[116:119], v[210:213], v[236:239], v[116:119]
	v_mfma_f32_16x16x32_bf16 v[104:107], v[196:199], v[244:247], v[104:107]
	v_mfma_f32_16x16x32_bf16 v[100:103], v[210:213], v[244:247], v[100:103]
	s_barrier
	ds_read_b128 v[216:219], v203 offset:49152
	ds_read_b128 v[220:223], v203 offset:50176
	ds_read_b128 v[224:227], v203 offset:51200
	ds_read_b128 v[228:231], v203 offset:52224
	ds_read_b128 v[232:235], v203 offset:53248
	ds_read_b128 v[236:239], v203 offset:54272
	ds_read_b128 v[240:243], v203 offset:55296
	ds_read_b128 v[244:247], v203 offset:56320
	s_add_u32 s34, s52, 0x8000
	s_addc_u32 s35, s53, 0
	s_add_i32 s54, s61, s0
	s_mov_b32 m0, s54
	s_nop 0
	global_load_lds_dwordx4 v180, s[34:35]
	s_add_i32 m0, s54, 0x2000
	v_lshl_add_u64 v[250:251], s[34:35], 0, v[184:185]
	s_add_u32 s34, s52, 0xc000
	s_addc_u32 s35, s53, 0
	s_add_i32 s52, s62, s0
	global_load_lds_dwordx4 v[250:251], off
	s_mov_b32 m0, s52
	v_lshl_add_u64 v[200:201], v[200:201], 0, s[92:93]
	global_load_lds_dwordx4 v180, s[34:35]
	s_add_i32 m0, s52, 0x2000
	s_nop 0
	global_load_lds_dwordx4 v184, s[34:35]
	s_mov_b32 m0, s91
	s_nop 0
	global_load_lds_dwordx4 v[200:201], off
	v_lshl_add_u64 v[200:201], v[248:249], 0, s[92:93]
	s_mov_b32 m0, s30
	s_nop 0
	global_load_lds_dwordx4 v[200:201], off
	s_waitcnt vmcnt(8) lgkmcnt(0)
	s_barrier
	v_mfma_f32_16x16x32_bf16 v[96:99], v[164:167], v[216:219], v[96:99]
	v_mfma_f32_16x16x32_bf16 v[92:95], v[172:175], v[216:219], v[92:95]
	v_mfma_f32_16x16x32_bf16 v[84:87], v[164:167], v[224:227], v[84:87]
	v_mfma_f32_16x16x32_bf16 v[76:79], v[172:175], v[224:227], v[76:79]
	v_mfma_f32_16x16x32_bf16 v[68:71], v[164:167], v[232:235], v[68:71]
	v_mfma_f32_16x16x32_bf16 v[60:63], v[172:175], v[232:235], v[60:63]
	v_mfma_f32_16x16x32_bf16 v[52:55], v[164:167], v[240:243], v[52:55]
	v_mfma_f32_16x16x32_bf16 v[44:47], v[172:175], v[240:243], v[44:47]
	v_mfma_f32_16x16x32_bf16 v[96:99], v[168:171], v[220:223], v[96:99]
	v_mfma_f32_16x16x32_bf16 v[92:95], v[176:179], v[220:223], v[92:95]
	v_mfma_f32_16x16x32_bf16 v[84:87], v[168:171], v[228:231], v[84:87]
	v_mfma_f32_16x16x32_bf16 v[76:79], v[176:179], v[228:231], v[76:79]
	v_mfma_f32_16x16x32_bf16 v[68:71], v[168:171], v[236:239], v[68:71]
	v_mfma_f32_16x16x32_bf16 v[60:63], v[176:179], v[236:239], v[60:63]
	v_mfma_f32_16x16x32_bf16 v[52:55], v[168:171], v[244:247], v[52:55]
	v_mfma_f32_16x16x32_bf16 v[44:47], v[176:179], v[244:247], v[44:47]
	v_mfma_f32_16x16x32_bf16 v[88:91], v[192:195], v[216:219], v[88:91]
	v_mfma_f32_16x16x32_bf16 v[80:83], v[204:207], v[216:219], v[80:83]
	v_mfma_f32_16x16x32_bf16 v[72:75], v[192:195], v[224:227], v[72:75]
	v_mfma_f32_16x16x32_bf16 v[64:67], v[204:207], v[224:227], v[64:67]
	v_mfma_f32_16x16x32_bf16 v[56:59], v[192:195], v[232:235], v[56:59]
	v_mfma_f32_16x16x32_bf16 v[48:51], v[204:207], v[232:235], v[48:51]
	v_mfma_f32_16x16x32_bf16 v[40:43], v[192:195], v[240:243], v[40:43]
	v_mfma_f32_16x16x32_bf16 v[36:39], v[204:207], v[240:243], v[36:39]
	v_mfma_f32_16x16x32_bf16 v[88:91], v[196:199], v[220:223], v[88:91]
	v_mfma_f32_16x16x32_bf16 v[80:83], v[210:213], v[220:223], v[80:83]
	v_mfma_f32_16x16x32_bf16 v[72:75], v[196:199], v[228:231], v[72:75]
	v_mfma_f32_16x16x32_bf16 v[64:67], v[210:213], v[228:231], v[64:67]
	v_mfma_f32_16x16x32_bf16 v[56:59], v[196:199], v[236:239], v[56:59]
	v_mfma_f32_16x16x32_bf16 v[48:51], v[210:213], v[236:239], v[48:51]
	v_mfma_f32_16x16x32_bf16 v[40:43], v[196:199], v[244:247], v[40:43]
	v_mfma_f32_16x16x32_bf16 v[36:39], v[210:213], v[244:247], v[36:39]
	s_add_i32 s60, s60, 2
	s_add_u32 s21, s21, 0x10000
	s_addc_u32 s59, s59, 0
	s_add_u32 s50, s50, 0x100
	s_addc_u32 s51, s51, 0
	s_cmp_gt_u32 s60, 5
	s_barrier
	s_cbranch_scc0 .LBB0_707
	s_and_b64 vcc, exec, s[46:47]
	s_cbranch_vccz .LBB0_710
	s_barrier

.LBB0_788:
	ds_read_b128 v[136:139], v200 offset:0
	ds_read_b128 v[140:143], v200 offset:1024
	ds_read_b128 v[144:147], v200 offset:2048
	ds_read_b128 v[148:151], v200 offset:3072
	ds_read_b128 v[152:155], v200 offset:16384
	ds_read_b128 v[156:159], v200 offset:17408
	ds_read_b128 v[160:163], v200 offset:18432
	ds_read_b128 v[174:177], v200 offset:19456
	ds_read_b128 v[178:181], v199
	ds_read_b128 v[182:185], v199 offset:1024
	ds_read_b128 v[186:189], v199 offset:2048
	ds_read_b128 v[190:193], v199 offset:3072
	ds_read_b128 v[194:197], v199 offset:4096
	ds_read_b128 v[210:213], v199 offset:5120
	ds_read_b128 v[240:243], v199 offset:6144
	ds_read_b128 v[244:247], v199 offset:7168
	s_add_u32 s34, s48, 0xfff80080
	s_addc_u32 s35, s49, -1
	s_add_i32 s57, 0, 0x10000
	s_cmp_eq_u32 s56, 28
	s_cselect_b32 s55, s23, s35
	s_cselect_b32 s54, s22, s34
	s_cselect_b32 s53, s43, s51
	s_cselect_b32 s52, s42, s15
	s_add_i32 s69, 0, 0x14000
	s_add_i32 m0, s29, 0xc000
	s_nop 0
	global_load_lds_dwordx4 v170, s[48:49]
	s_add_i32 m0, s29, 0xe000
	s_nop 0
	global_load_lds_dwordx4 v172, s[48:49]
	s_waitcnt vmcnt(8) lgkmcnt(0)
	s_barrier
	v_mfma_f32_16x16x32_bf16 v[132:135], v[136:139], v[178:181], v[132:135]
	v_mfma_f32_16x16x32_bf16 v[128:131], v[144:147], v[178:181], v[128:131]
	v_mfma_f32_16x16x32_bf16 v[124:127], v[136:139], v[186:189], v[124:127]
	v_mfma_f32_16x16x32_bf16 v[120:123], v[144:147], v[186:189], v[120:123]
	v_mfma_f32_16x16x32_bf16 v[116:119], v[136:139], v[194:197], v[116:119]
	v_mfma_f32_16x16x32_bf16 v[112:115], v[144:147], v[194:197], v[112:115]
	v_mfma_f32_16x16x32_bf16 v[108:111], v[136:139], v[240:243], v[108:111]
	v_mfma_f32_16x16x32_bf16 v[104:107], v[144:147], v[240:243], v[104:107]
	v_mfma_f32_16x16x32_bf16 v[132:135], v[140:143], v[182:185], v[132:135]
	v_mfma_f32_16x16x32_bf16 v[128:131], v[148:151], v[182:185], v[128:131]
	v_mfma_f32_16x16x32_bf16 v[124:127], v[140:143], v[190:193], v[124:127]
	v_mfma_f32_16x16x32_bf16 v[120:123], v[148:151], v[190:193], v[120:123]
	v_mfma_f32_16x16x32_bf16 v[116:119], v[140:143], v[210:213], v[116:119]
	v_mfma_f32_16x16x32_bf16 v[112:115], v[148:151], v[210:213], v[112:115]
	v_mfma_f32_16x16x32_bf16 v[108:111], v[140:143], v[244:247], v[108:111]
	v_mfma_f32_16x16x32_bf16 v[104:107], v[148:151], v[244:247], v[104:107]
	v_mfma_f32_16x16x32_bf16 v[100:103], v[152:155], v[178:181], v[100:103]
	v_mfma_f32_16x16x32_bf16 v[96:99], v[160:163], v[178:181], v[96:99]
	v_mfma_f32_16x16x32_bf16 v[92:95], v[152:155], v[186:189], v[92:95]
	v_mfma_f32_16x16x32_bf16 v[88:91], v[160:163], v[186:189], v[88:91]
	v_mfma_f32_16x16x32_bf16 v[84:87], v[152:155], v[194:197], v[84:87]
	v_mfma_f32_16x16x32_bf16 v[80:83], v[160:163], v[194:197], v[80:83]
	v_mfma_f32_16x16x32_bf16 v[72:75], v[152:155], v[240:243], v[72:75]
	v_mfma_f32_16x16x32_bf16 v[64:67], v[160:163], v[240:243], v[64:67]
	v_mfma_f32_16x16x32_bf16 v[100:103], v[156:159], v[182:185], v[100:103]
	v_mfma_f32_16x16x32_bf16 v[96:99], v[174:177], v[182:185], v[96:99]
	v_mfma_f32_16x16x32_bf16 v[92:95], v[156:159], v[190:193], v[92:95]
	v_mfma_f32_16x16x32_bf16 v[88:91], v[174:177], v[190:193], v[88:91]
	v_mfma_f32_16x16x32_bf16 v[84:87], v[156:159], v[210:213], v[84:87]
	v_mfma_f32_16x16x32_bf16 v[80:83], v[174:177], v[210:213], v[80:83]
	v_mfma_f32_16x16x32_bf16 v[72:75], v[156:159], v[244:247], v[72:75]
	v_mfma_f32_16x16x32_bf16 v[64:67], v[174:177], v[244:247], v[64:67]
	s_barrier
	ds_read_b128 v[178:181], v199 offset:16384
	ds_read_b128 v[182:185], v199 offset:17408
	ds_read_b128 v[186:189], v199 offset:18432
	ds_read_b128 v[190:193], v199 offset:19456
	ds_read_b128 v[194:197], v199 offset:20480
	ds_read_b128 v[210:213], v199 offset:21504
	ds_read_b128 v[240:243], v199 offset:22528
	ds_read_b128 v[244:247], v199 offset:23552
	s_add_i32 s34, s57, s0
	s_mov_b32 m0, s34
	s_nop 0
	global_load_lds_dwordx4 v32, s[52:53]
	s_add_i32 m0, s34, 0x2000
	s_add_u32 s34, s52, 0x4000
	s_addc_u32 s35, s53, 0
	s_add_i32 s57, s69, s0
	global_load_lds_dwordx4 v166, s[52:53]
	s_mov_b32 m0, s57
	v_lshl_add_u64 v[248:249], s[54:55], 0, v[164:165]
	global_load_lds_dwordx4 v32, s[34:35]
	s_add_i32 m0, s57, 0x2000
	v_lshl_add_u64 v[250:251], s[54:55], 0, v[168:169]
	global_load_lds_dwordx4 v166, s[34:35]
	s_mov_b32 m0, s29
	s_nop 0
	global_load_lds_dwordx4 v164, s[54:55]
	s_mov_b32 m0, s45
	s_nop 0
	global_load_lds_dwordx4 v168, s[54:55]
	s_waitcnt vmcnt(8) lgkmcnt(0)
	s_barrier
	v_mfma_f32_16x16x32_bf16 v[76:79], v[136:139], v[178:181], v[76:79]
	v_mfma_f32_16x16x32_bf16 v[68:71], v[144:147], v[178:181], v[68:71]
	v_mfma_f32_16x16x32_bf16 v[60:63], v[136:139], v[186:189], v[60:63]
	v_mfma_f32_16x16x32_bf16 v[56:59], v[144:147], v[186:189], v[56:59]
	v_mfma_f32_16x16x32_bf16 v[52:55], v[136:139], v[194:197], v[52:55]
	v_mfma_f32_16x16x32_bf16 v[48:51], v[144:147], v[194:197], v[48:51]
	v_mfma_f32_16x16x32_bf16 v[44:47], v[136:139], v[240:243], v[44:47]
	v_mfma_f32_16x16x32_bf16 v[40:43], v[144:147], v[240:243], v[40:43]
	v_mfma_f32_16x16x32_bf16 v[76:79], v[140:143], v[182:185], v[76:79]
	v_mfma_f32_16x16x32_bf16 v[68:71], v[148:151], v[182:185], v[68:71]
	v_mfma_f32_16x16x32_bf16 v[60:63], v[140:143], v[190:193], v[60:63]
	v_mfma_f32_16x16x32_bf16 v[56:59], v[148:151], v[190:193], v[56:59]
	v_mfma_f32_16x16x32_bf16 v[52:55], v[140:143], v[210:213], v[52:55]
	v_mfma_f32_16x16x32_bf16 v[48:51], v[148:151], v[210:213], v[48:51]
	v_mfma_f32_16x16x32_bf16 v[44:47], v[140:143], v[244:247], v[44:47]
	v_mfma_f32_16x16x32_bf16 v[40:43], v[148:151], v[244:247], v[40:43]
	v_mfma_f32_16x16x32_bf16 v[36:39], v[152:155], v[178:181], v[36:39]
	v_mfma_f32_16x16x32_bf16 v[28:31], v[160:163], v[178:181], v[28:31]
	v_mfma_f32_16x16x32_bf16 v[24:27], v[152:155], v[186:189], v[24:27]
	v_mfma_f32_16x16x32_bf16 v[20:23], v[160:163], v[186:189], v[20:23]
	v_mfma_f32_16x16x32_bf16 v[16:19], v[152:155], v[194:197], v[16:19]
	v_mfma_f32_16x16x32_bf16 v[12:15], v[160:163], v[194:197], v[12:15]
	v_mfma_f32_16x16x32_bf16 v[8:11], v[152:155], v[240:243], v[8:11]
	v_mfma_f32_16x16x32_bf16 v[2:5], v[160:163], v[240:243], v[4:7]
	v_mfma_f32_16x16x32_bf16 v[36:39], v[156:159], v[182:185], v[36:39]
	v_mfma_f32_16x16x32_bf16 v[28:31], v[174:177], v[182:185], v[28:31]
	v_mfma_f32_16x16x32_bf16 v[24:27], v[156:159], v[190:193], v[24:27]
	v_mfma_f32_16x16x32_bf16 v[20:23], v[174:177], v[190:193], v[20:23]
	v_mfma_f32_16x16x32_bf16 v[16:19], v[156:159], v[210:213], v[16:19]
	v_mfma_f32_16x16x32_bf16 v[12:15], v[174:177], v[210:213], v[12:15]
	v_mfma_f32_16x16x32_bf16 v[8:11], v[156:159], v[244:247], v[8:11]
	v_mfma_f32_16x16x32_bf16 v[2:5], v[174:177], v[244:247], v[2:5]
	s_barrier
	ds_read_b128 v[136:139], v200 offset:32768
	ds_read_b128 v[140:143], v200 offset:33792
	ds_read_b128 v[144:147], v200 offset:34816
	ds_read_b128 v[148:151], v200 offset:35840
	ds_read_b128 v[152:155], v200 offset:49152
	ds_read_b128 v[156:159], v200 offset:50176
	ds_read_b128 v[160:163], v200 offset:51200
	ds_read_b128 v[174:177], v200 offset:52224
	ds_read_b128 v[178:181], v199 offset:32768
	ds_read_b128 v[182:185], v199 offset:33792
	ds_read_b128 v[186:189], v199 offset:34816
	ds_read_b128 v[190:193], v199 offset:35840
	ds_read_b128 v[194:197], v199 offset:36864
	ds_read_b128 v[210:213], v199 offset:37888
	ds_read_b128 v[240:243], v199 offset:38912
	ds_read_b128 v[244:247], v199 offset:39936
	s_add_i32 s57, 0, 0x18000
	s_add_i32 s69, 0, 0x1c000
	s_add_u32 s34, s54, 0x80000
	s_addc_u32 s35, s55, 0
	s_mov_b32 m0, s82
	s_nop 0
	global_load_lds_dwordx4 v164, s[34:35]
	s_mov_b32 m0, s90
	s_nop 0
	global_load_lds_dwordx4 v168, s[34:35]
	s_waitcnt vmcnt(8) lgkmcnt(0)
	s_barrier
	v_mfma_f32_16x16x32_bf16 v[132:135], v[136:139], v[178:181], v[132:135]
	v_mfma_f32_16x16x32_bf16 v[128:131], v[144:147], v[178:181], v[128:131]
	v_mfma_f32_16x16x32_bf16 v[124:127], v[136:139], v[186:189], v[124:127]
	v_mfma_f32_16x16x32_bf16 v[120:123], v[144:147], v[186:189], v[120:123]
	v_mfma_f32_16x16x32_bf16 v[116:119], v[136:139], v[194:197], v[116:119]
	v_mfma_f32_16x16x32_bf16 v[112:115], v[144:147], v[194:197], v[112:115]
	v_mfma_f32_16x16x32_bf16 v[108:111], v[136:139], v[240:243], v[108:111]
	v_mfma_f32_16x16x32_bf16 v[104:107], v[144:147], v[240:243], v[104:107]
	v_mfma_f32_16x16x32_bf16 v[132:135], v[140:143], v[182:185], v[132:135]
	v_mfma_f32_16x16x32_bf16 v[128:131], v[148:151], v[182:185], v[128:131]
	v_mfma_f32_16x16x32_bf16 v[124:127], v[140:143], v[190:193], v[124:127]
	v_mfma_f32_16x16x32_bf16 v[120:123], v[148:151], v[190:193], v[120:123]
	v_mfma_f32_16x16x32_bf16 v[116:119], v[140:143], v[210:213], v[116:119]
	v_mfma_f32_16x16x32_bf16 v[112:115], v[148:151], v[210:213], v[112:115]
	v_mfma_f32_16x16x32_bf16 v[108:111], v[140:143], v[244:247], v[108:111]
	v_mfma_f32_16x16x32_bf16 v[104:107], v[148:151], v[244:247], v[104:107]
	v_mfma_f32_16x16x32_bf16 v[100:103], v[152:155], v[178:181], v[100:103]
	v_mfma_f32_16x16x32_bf16 v[96:99], v[160:163], v[178:181], v[96:99]
	v_mfma_f32_16x16x32_bf16 v[92:95], v[152:155], v[186:189], v[92:95]
	v_mfma_f32_16x16x32_bf16 v[88:91], v[160:163], v[186:189], v[88:91]
	v_mfma_f32_16x16x32_bf16 v[84:87], v[152:155], v[194:197], v[84:87]
	v_mfma_f32_16x16x32_bf16 v[80:83], v[160:163], v[194:197], v[80:83]
	v_mfma_f32_16x16x32_bf16 v[72:75], v[152:155], v[240:243], v[72:75]
	v_mfma_f32_16x16x32_bf16 v[64:67], v[160:163], v[240:243], v[64:67]
	v_mfma_f32_16x16x32_bf16 v[100:103], v[156:159], v[182:185], v[100:103]
	v_mfma_f32_16x16x32_bf16 v[96:99], v[174:177], v[182:185], v[96:99]
	v_mfma_f32_16x16x32_bf16 v[92:95], v[156:159], v[190:193], v[92:95]
	v_mfma_f32_16x16x32_bf16 v[88:91], v[174:177], v[190:193], v[88:91]
	v_mfma_f32_16x16x32_bf16 v[84:87], v[156:159], v[210:213], v[84:87]
	v_mfma_f32_16x16x32_bf16 v[80:83], v[174:177], v[210:213], v[80:83]
	v_mfma_f32_16x16x32_bf16 v[72:75], v[156:159], v[244:247], v[72:75]
	v_mfma_f32_16x16x32_bf16 v[64:67], v[174:177], v[244:247], v[64:67]
	s_barrier
	ds_read_b128 v[178:181], v199 offset:49152
	ds_read_b128 v[182:185], v199 offset:50176
	ds_read_b128 v[186:189], v199 offset:51200
	ds_read_b128 v[190:193], v199 offset:52224
	ds_read_b128 v[194:197], v199 offset:53248
	ds_read_b128 v[210:213], v199 offset:54272
	ds_read_b128 v[240:243], v199 offset:55296
	ds_read_b128 v[244:247], v199 offset:56320
	s_add_u32 s34, s52, 0x8000
	s_addc_u32 s35, s53, 0
	s_add_i32 s54, s57, s0
	s_mov_b32 m0, s54
	s_nop 0
	global_load_lds_dwordx4 v32, s[34:35]
	s_add_i32 m0, s54, 0x2000
	v_lshl_add_u64 v[6:7], s[34:35], 0, v[166:167]
	s_add_u32 s34, s52, 0xc000
	s_addc_u32 s35, s53, 0
	s_add_i32 s52, s69, s0
	global_load_lds_dwordx4 v[6:7], off
	s_mov_b32 m0, s52
	s_nop 0
	global_load_lds_dwordx4 v32, s[34:35]
	s_add_i32 m0, s52, 0x2000
	s_nop 0
	global_load_lds_dwordx4 v166, s[34:35]
	v_lshl_add_u64 v[6:7], v[248:249], 0, s[92:93]
	s_mov_b32 m0, s91
	s_nop 0
	global_load_lds_dwordx4 v[6:7], off
	v_lshl_add_u64 v[6:7], v[250:251], 0, s[92:93]
	s_mov_b32 m0, s30
	s_nop 0
	global_load_lds_dwordx4 v[6:7], off
	s_waitcnt vmcnt(8) lgkmcnt(0)
	s_barrier
	v_mfma_f32_16x16x32_bf16 v[76:79], v[136:139], v[178:181], v[76:79]
	v_mfma_f32_16x16x32_bf16 v[68:71], v[144:147], v[178:181], v[68:71]
	v_mfma_f32_16x16x32_bf16 v[60:63], v[136:139], v[186:189], v[60:63]
	v_mfma_f32_16x16x32_bf16 v[56:59], v[144:147], v[186:189], v[56:59]
	v_mfma_f32_16x16x32_bf16 v[52:55], v[136:139], v[194:197], v[52:55]
	v_mfma_f32_16x16x32_bf16 v[48:51], v[144:147], v[194:197], v[48:51]
	v_mfma_f32_16x16x32_bf16 v[44:47], v[136:139], v[240:243], v[44:47]
	v_mfma_f32_16x16x32_bf16 v[40:43], v[144:147], v[240:243], v[40:43]
	v_mfma_f32_16x16x32_bf16 v[76:79], v[140:143], v[182:185], v[76:79]
	v_mfma_f32_16x16x32_bf16 v[68:71], v[148:151], v[182:185], v[68:71]
	v_mfma_f32_16x16x32_bf16 v[60:63], v[140:143], v[190:193], v[60:63]
	v_mfma_f32_16x16x32_bf16 v[56:59], v[148:151], v[190:193], v[56:59]
	v_mfma_f32_16x16x32_bf16 v[52:55], v[140:143], v[210:213], v[52:55]
	v_mfma_f32_16x16x32_bf16 v[48:51], v[148:151], v[210:213], v[48:51]
	v_mfma_f32_16x16x32_bf16 v[44:47], v[140:143], v[244:247], v[44:47]
	v_mfma_f32_16x16x32_bf16 v[40:43], v[148:151], v[244:247], v[40:43]
	v_mfma_f32_16x16x32_bf16 v[36:39], v[152:155], v[178:181], v[36:39]
	v_mfma_f32_16x16x32_bf16 v[28:31], v[160:163], v[178:181], v[28:31]
	v_mfma_f32_16x16x32_bf16 v[24:27], v[152:155], v[186:189], v[24:27]
	v_mfma_f32_16x16x32_bf16 v[20:23], v[160:163], v[186:189], v[20:23]
	v_mfma_f32_16x16x32_bf16 v[16:19], v[152:155], v[194:197], v[16:19]
	v_mfma_f32_16x16x32_bf16 v[12:15], v[160:163], v[194:197], v[12:15]
	v_mfma_f32_16x16x32_bf16 v[6:9], v[152:155], v[240:243], v[8:11]
	v_mfma_f32_16x16x32_bf16 v[2:5], v[160:163], v[240:243], v[2:5]
	v_mfma_f32_16x16x32_bf16 v[36:39], v[156:159], v[182:185], v[36:39]
	v_mfma_f32_16x16x32_bf16 v[28:31], v[174:177], v[182:185], v[28:31]
	v_mfma_f32_16x16x32_bf16 v[24:27], v[156:159], v[190:193], v[24:27]
	v_mfma_f32_16x16x32_bf16 v[20:23], v[174:177], v[190:193], v[20:23]
	v_mfma_f32_16x16x32_bf16 v[16:19], v[156:159], v[210:213], v[16:19]
	v_mfma_f32_16x16x32_bf16 v[12:15], v[174:177], v[210:213], v[12:15]
	v_mfma_f32_16x16x32_bf16 v[8:11], v[156:159], v[244:247], v[6:9]
	v_mfma_f32_16x16x32_bf16 v[4:7], v[174:177], v[244:247], v[2:5]
	s_add_i32 s56, s56, 2
	s_add_u32 s15, s15, 0x10000
	s_addc_u32 s51, s51, 0
	s_add_u32 s48, s48, 0x100
	s_addc_u32 s49, s49, 0
	s_cmp_gt_u32 s56, 29
	s_barrier
	s_cbranch_scc0 .LBB0_788
	s_and_b64 vcc, exec, s[46:47]
	s_cbranch_vccz .LBB0_791
	s_barrier

.LBB0_877:
	ds_read_b128 v[132:135], v190 offset:0
	ds_read_b128 v[136:139], v190 offset:1024
	ds_read_b128 v[140:143], v190 offset:2048
	ds_read_b128 v[144:147], v190 offset:3072
	ds_read_b128 v[148:151], v190 offset:16384
	ds_read_b128 v[152:155], v190 offset:17408
	ds_read_b128 v[168:171], v190 offset:18432
	ds_read_b128 v[172:175], v190 offset:19456
	ds_read_b128 v[176:179], v189
	ds_read_b128 v[180:183], v189 offset:1024
	ds_read_b128 v[184:187], v189 offset:2048
	ds_read_b128 v[192:195], v189 offset:3072
	ds_read_b128 v[210:213], v189 offset:4096
	ds_read_b128 v[234:237], v189 offset:5120
	ds_read_b128 v[238:241], v189 offset:6144
	ds_read_b128 v[242:245], v189 offset:7168
	s_add_u32 s62, s60, 0x100
	s_addc_u32 s63, s61, 0
	s_add_i32 s34, 0, 0x10000
	s_cmp_eq_u32 s49, 60
	s_cselect_b32 s67, s51, s63
	s_cselect_b32 s66, s50, s62
	s_cselect_b32 s65, s53, s28
	s_cselect_b32 s64, s52, s13
	s_add_i32 s55, 0, 0x14000
	s_add_i32 m0, s29, 0xc000
	s_nop 0
	global_load_lds_dwordx4 v164, s[60:61]
	s_add_i32 m0, s29, 0xe000
	s_nop 0
	global_load_lds_dwordx4 v166, s[60:61]
	s_waitcnt vmcnt(8) lgkmcnt(0)
	s_barrier
	v_mfma_f32_16x16x32_bf16 v[128:131], v[132:135], v[176:179], v[128:131]
	v_mfma_f32_16x16x32_bf16 v[124:127], v[140:143], v[176:179], v[124:127]
	v_mfma_f32_16x16x32_bf16 v[112:115], v[132:135], v[184:187], v[112:115]
	v_mfma_f32_16x16x32_bf16 v[108:111], v[140:143], v[184:187], v[108:111]
	v_mfma_f32_16x16x32_bf16 v[96:99], v[132:135], v[210:213], v[96:99]
	v_mfma_f32_16x16x32_bf16 v[92:95], v[140:143], v[210:213], v[92:95]
	v_mfma_f32_16x16x32_bf16 v[80:83], v[132:135], v[238:241], v[80:83]
	v_mfma_f32_16x16x32_bf16 v[76:79], v[140:143], v[238:241], v[76:79]
	v_mfma_f32_16x16x32_bf16 v[128:131], v[136:139], v[180:183], v[128:131]
	v_mfma_f32_16x16x32_bf16 v[124:127], v[144:147], v[180:183], v[124:127]
	v_mfma_f32_16x16x32_bf16 v[112:115], v[136:139], v[192:195], v[112:115]
	v_mfma_f32_16x16x32_bf16 v[108:111], v[144:147], v[192:195], v[108:111]
	v_mfma_f32_16x16x32_bf16 v[96:99], v[136:139], v[234:237], v[96:99]
	v_mfma_f32_16x16x32_bf16 v[92:95], v[144:147], v[234:237], v[92:95]
	v_mfma_f32_16x16x32_bf16 v[80:83], v[136:139], v[242:245], v[80:83]
	v_mfma_f32_16x16x32_bf16 v[76:79], v[144:147], v[242:245], v[76:79]
	v_mfma_f32_16x16x32_bf16 v[120:123], v[148:151], v[176:179], v[120:123]
	v_mfma_f32_16x16x32_bf16 v[116:119], v[168:171], v[176:179], v[116:119]
	v_mfma_f32_16x16x32_bf16 v[104:107], v[148:151], v[184:187], v[104:107]
	v_mfma_f32_16x16x32_bf16 v[100:103], v[168:171], v[184:187], v[100:103]
	v_mfma_f32_16x16x32_bf16 v[88:91], v[148:151], v[210:213], v[88:91]
	v_mfma_f32_16x16x32_bf16 v[84:87], v[168:171], v[210:213], v[84:87]
	v_mfma_f32_16x16x32_bf16 v[72:75], v[148:151], v[238:241], v[72:75]
	v_mfma_f32_16x16x32_bf16 v[68:71], v[168:171], v[238:241], v[68:71]
	v_mfma_f32_16x16x32_bf16 v[120:123], v[152:155], v[180:183], v[120:123]
	v_mfma_f32_16x16x32_bf16 v[116:119], v[172:175], v[180:183], v[116:119]
	v_mfma_f32_16x16x32_bf16 v[104:107], v[152:155], v[192:195], v[104:107]
	v_mfma_f32_16x16x32_bf16 v[100:103], v[172:175], v[192:195], v[100:103]
	v_mfma_f32_16x16x32_bf16 v[88:91], v[152:155], v[234:237], v[88:91]
	v_mfma_f32_16x16x32_bf16 v[84:87], v[172:175], v[234:237], v[84:87]
	v_mfma_f32_16x16x32_bf16 v[72:75], v[152:155], v[242:245], v[72:75]
	v_mfma_f32_16x16x32_bf16 v[68:71], v[172:175], v[242:245], v[68:71]
	s_barrier
	ds_read_b128 v[176:179], v189 offset:16384
	ds_read_b128 v[180:183], v189 offset:17408
	ds_read_b128 v[184:187], v189 offset:18432
	ds_read_b128 v[192:195], v189 offset:19456
	ds_read_b128 v[210:213], v189 offset:20480
	ds_read_b128 v[234:237], v189 offset:21504
	ds_read_b128 v[238:241], v189 offset:22528
	ds_read_b128 v[242:245], v189 offset:23552
	s_add_i32 s34, s34, s0
	s_mov_b32 m0, s34
	s_nop 0
	global_load_lds_dwordx4 v156, s[64:65]
	s_add_i32 m0, s34, 0x2000
	s_add_u32 s34, s64, 0x4000
	s_addc_u32 s35, s65, 0
	s_add_i32 s55, s55, s0
	global_load_lds_dwordx4 v160, s[64:65]
	s_mov_b32 m0, s55
	s_nop 0
	global_load_lds_dwordx4 v156, s[34:35]
	s_add_i32 m0, s55, 0x2000
	s_nop 0
	global_load_lds_dwordx4 v160, s[34:35]
	s_mov_b32 m0, s29
	s_nop 0
	global_load_lds_dwordx4 v158, s[66:67]
	s_mov_b32 m0, s45
	s_nop 0
	global_load_lds_dwordx4 v162, s[66:67]
	s_waitcnt vmcnt(8) lgkmcnt(0)
	s_barrier
	v_mfma_f32_16x16x32_bf16 v[64:67], v[132:135], v[176:179], v[64:67]
	v_mfma_f32_16x16x32_bf16 v[60:63], v[140:143], v[176:179], v[60:63]
	v_mfma_f32_16x16x32_bf16 v[48:51], v[132:135], v[184:187], v[48:51]
	v_mfma_f32_16x16x32_bf16 v[44:47], v[140:143], v[184:187], v[44:47]
	v_mfma_f32_16x16x32_bf16 v[30:33], v[132:135], v[210:213], v[30:33]
	v_mfma_f32_16x16x32_bf16 v[26:29], v[140:143], v[210:213], v[26:29]
	v_mfma_f32_16x16x32_bf16 v[14:17], v[132:135], v[238:241], v[14:17]
	v_mfma_f32_16x16x32_bf16 v[10:13], v[140:143], v[238:241], v[10:13]
	v_mfma_f32_16x16x32_bf16 v[64:67], v[136:139], v[180:183], v[64:67]
	v_mfma_f32_16x16x32_bf16 v[60:63], v[144:147], v[180:183], v[60:63]
	v_mfma_f32_16x16x32_bf16 v[48:51], v[136:139], v[192:195], v[48:51]
	v_mfma_f32_16x16x32_bf16 v[44:47], v[144:147], v[192:195], v[44:47]
	v_mfma_f32_16x16x32_bf16 v[30:33], v[136:139], v[234:237], v[30:33]
	v_mfma_f32_16x16x32_bf16 v[26:29], v[144:147], v[234:237], v[26:29]
	v_mfma_f32_16x16x32_bf16 v[14:17], v[136:139], v[242:245], v[14:17]
	v_mfma_f32_16x16x32_bf16 v[10:13], v[144:147], v[242:245], v[10:13]
	v_mfma_f32_16x16x32_bf16 v[56:59], v[148:151], v[176:179], v[56:59]
	v_mfma_f32_16x16x32_bf16 v[52:55], v[168:171], v[176:179], v[52:55]
	v_mfma_f32_16x16x32_bf16 v[40:43], v[148:151], v[184:187], v[40:43]
	v_mfma_f32_16x16x32_bf16 v[36:39], v[168:171], v[184:187], v[36:39]
	v_mfma_f32_16x16x32_bf16 v[22:25], v[148:151], v[210:213], v[22:25]
	v_mfma_f32_16x16x32_bf16 v[18:21], v[168:171], v[210:213], v[18:21]
	v_mfma_f32_16x16x32_bf16 v[6:9], v[148:151], v[238:241], v[6:9]
	v_mfma_f32_16x16x32_bf16 v[2:5], v[168:171], v[238:241], v[2:5]
	v_mfma_f32_16x16x32_bf16 v[56:59], v[152:155], v[180:183], v[56:59]
	v_mfma_f32_16x16x32_bf16 v[52:55], v[172:175], v[180:183], v[52:55]
	v_mfma_f32_16x16x32_bf16 v[40:43], v[152:155], v[192:195], v[40:43]
	v_mfma_f32_16x16x32_bf16 v[36:39], v[172:175], v[192:195], v[36:39]
	v_mfma_f32_16x16x32_bf16 v[22:25], v[152:155], v[234:237], v[22:25]
	v_mfma_f32_16x16x32_bf16 v[18:21], v[172:175], v[234:237], v[18:21]
	v_mfma_f32_16x16x32_bf16 v[6:9], v[152:155], v[242:245], v[6:9]
	v_mfma_f32_16x16x32_bf16 v[2:5], v[172:175], v[242:245], v[2:5]
	s_barrier
	ds_read_b128 v[132:135], v190 offset:32768
	ds_read_b128 v[136:139], v190 offset:33792
	ds_read_b128 v[140:143], v190 offset:34816
	ds_read_b128 v[144:147], v190 offset:35840
	ds_read_b128 v[148:151], v190 offset:49152
	ds_read_b128 v[152:155], v190 offset:50176
	ds_read_b128 v[168:171], v190 offset:51200
	ds_read_b128 v[172:175], v190 offset:52224
	ds_read_b128 v[176:179], v189 offset:32768
	ds_read_b128 v[180:183], v189 offset:33792
	ds_read_b128 v[184:187], v189 offset:34816
	ds_read_b128 v[192:195], v189 offset:35840
	ds_read_b128 v[210:213], v189 offset:36864
	ds_read_b128 v[234:237], v189 offset:37888
	ds_read_b128 v[238:241], v189 offset:38912
	ds_read_b128 v[242:245], v189 offset:39936
	s_add_i32 s55, 0, 0x18000
	s_add_i32 s58, 0, 0x1c000
	s_add_u32 s34, s66, 0x100000
	s_addc_u32 s35, s67, 0
	s_mov_b32 m0, s82
	s_nop 0
	global_load_lds_dwordx4 v158, s[34:35]
	s_mov_b32 m0, s90
	s_nop 0
	global_load_lds_dwordx4 v162, s[34:35]
	s_waitcnt vmcnt(8) lgkmcnt(0)
	s_barrier
	v_mfma_f32_16x16x32_bf16 v[128:131], v[132:135], v[176:179], v[128:131]
	v_mfma_f32_16x16x32_bf16 v[124:127], v[140:143], v[176:179], v[124:127]
	v_mfma_f32_16x16x32_bf16 v[112:115], v[132:135], v[184:187], v[112:115]
	v_mfma_f32_16x16x32_bf16 v[108:111], v[140:143], v[184:187], v[108:111]
	v_mfma_f32_16x16x32_bf16 v[96:99], v[132:135], v[210:213], v[96:99]
	v_mfma_f32_16x16x32_bf16 v[92:95], v[140:143], v[210:213], v[92:95]
	v_mfma_f32_16x16x32_bf16 v[80:83], v[132:135], v[238:241], v[80:83]
	v_mfma_f32_16x16x32_bf16 v[76:79], v[140:143], v[238:241], v[76:79]
	v_mfma_f32_16x16x32_bf16 v[128:131], v[136:139], v[180:183], v[128:131]
	v_mfma_f32_16x16x32_bf16 v[124:127], v[144:147], v[180:183], v[124:127]
	v_mfma_f32_16x16x32_bf16 v[112:115], v[136:139], v[192:195], v[112:115]
	v_mfma_f32_16x16x32_bf16 v[108:111], v[144:147], v[192:195], v[108:111]
	v_mfma_f32_16x16x32_bf16 v[96:99], v[136:139], v[234:237], v[96:99]
	v_mfma_f32_16x16x32_bf16 v[92:95], v[144:147], v[234:237], v[92:95]
	v_mfma_f32_16x16x32_bf16 v[80:83], v[136:139], v[242:245], v[80:83]
	v_mfma_f32_16x16x32_bf16 v[76:79], v[144:147], v[242:245], v[76:79]
	v_mfma_f32_16x16x32_bf16 v[120:123], v[148:151], v[176:179], v[120:123]
	v_mfma_f32_16x16x32_bf16 v[116:119], v[168:171], v[176:179], v[116:119]
	v_mfma_f32_16x16x32_bf16 v[104:107], v[148:151], v[184:187], v[104:107]
	v_mfma_f32_16x16x32_bf16 v[100:103], v[168:171], v[184:187], v[100:103]
	v_mfma_f32_16x16x32_bf16 v[88:91], v[148:151], v[210:213], v[88:91]
	v_mfma_f32_16x16x32_bf16 v[84:87], v[168:171], v[210:213], v[84:87]
	v_mfma_f32_16x16x32_bf16 v[72:75], v[148:151], v[238:241], v[72:75]
	v_mfma_f32_16x16x32_bf16 v[68:71], v[168:171], v[238:241], v[68:71]
	v_mfma_f32_16x16x32_bf16 v[120:123], v[152:155], v[180:183], v[120:123]
	v_mfma_f32_16x16x32_bf16 v[116:119], v[172:175], v[180:183], v[116:119]
	v_mfma_f32_16x16x32_bf16 v[104:107], v[152:155], v[192:195], v[104:107]
	v_mfma_f32_16x16x32_bf16 v[100:103], v[172:175], v[192:195], v[100:103]
	v_mfma_f32_16x16x32_bf16 v[88:91], v[152:155], v[234:237], v[88:91]
	v_mfma_f32_16x16x32_bf16 v[84:87], v[172:175], v[234:237], v[84:87]
	v_mfma_f32_16x16x32_bf16 v[72:75], v[152:155], v[242:245], v[72:75]
	v_mfma_f32_16x16x32_bf16 v[68:71], v[172:175], v[242:245], v[68:71]
	s_barrier
	ds_read_b128 v[176:179], v189 offset:49152
	ds_read_b128 v[180:183], v189 offset:50176
	ds_read_b128 v[184:187], v189 offset:51200
	ds_read_b128 v[192:195], v189 offset:52224
	ds_read_b128 v[210:213], v189 offset:53248
	ds_read_b128 v[234:237], v189 offset:54272
	ds_read_b128 v[238:241], v189 offset:55296
	ds_read_b128 v[242:245], v189 offset:56320
	s_add_u32 s34, s64, 0x8000
	s_addc_u32 s35, s65, 0
	s_add_i32 s55, s55, s0
	s_mov_b32 m0, s55
	s_nop 0
	global_load_lds_dwordx4 v156, s[34:35]
	s_add_i32 m0, s55, 0x2000
	s_mov_b64 s[100:101], s[34:35]
	s_add_u32 s34, s64, 0xc000
	s_addc_u32 s35, s65, 0
	s_add_i32 s55, s58, s0
	global_load_lds_dwordx4 v160, s[100:101]
	s_mov_b32 m0, s55
	s_nop 0
	global_load_lds_dwordx4 v156, s[34:35]
	s_add_i32 m0, s55, 0x2000
	s_nop 0
	global_load_lds_dwordx4 v160, s[34:35]
	s_mov_b32 m0, s91
	s_nop 0
	s_add_u32 s100, s66, s92
	s_addc_u32 s101, s67, s93
	global_load_lds_dwordx4 v158, s[100:101]
	s_mov_b32 m0, s30
	s_nop 0
	s_add_u32 s100, s66, s92
	s_addc_u32 s101, s67, s93
	global_load_lds_dwordx4 v162, s[100:101]
	s_waitcnt vmcnt(8) lgkmcnt(0)
	s_barrier
	v_mfma_f32_16x16x32_bf16 v[64:67], v[132:135], v[176:179], v[64:67]
	v_mfma_f32_16x16x32_bf16 v[60:63], v[140:143], v[176:179], v[60:63]
	v_mfma_f32_16x16x32_bf16 v[48:51], v[132:135], v[184:187], v[48:51]
	v_mfma_f32_16x16x32_bf16 v[44:47], v[140:143], v[184:187], v[44:47]
	v_mfma_f32_16x16x32_bf16 v[30:33], v[132:135], v[210:213], v[30:33]
	v_mfma_f32_16x16x32_bf16 v[26:29], v[140:143], v[210:213], v[26:29]
	v_mfma_f32_16x16x32_bf16 v[14:17], v[132:135], v[238:241], v[14:17]
	v_mfma_f32_16x16x32_bf16 v[10:13], v[140:143], v[238:241], v[10:13]
	v_mfma_f32_16x16x32_bf16 v[64:67], v[136:139], v[180:183], v[64:67]
	v_mfma_f32_16x16x32_bf16 v[60:63], v[144:147], v[180:183], v[60:63]
	v_mfma_f32_16x16x32_bf16 v[48:51], v[136:139], v[192:195], v[48:51]
	v_mfma_f32_16x16x32_bf16 v[44:47], v[144:147], v[192:195], v[44:47]
	v_mfma_f32_16x16x32_bf16 v[30:33], v[136:139], v[234:237], v[30:33]
	v_mfma_f32_16x16x32_bf16 v[26:29], v[144:147], v[234:237], v[26:29]
	v_mfma_f32_16x16x32_bf16 v[14:17], v[136:139], v[242:245], v[14:17]
	v_mfma_f32_16x16x32_bf16 v[10:13], v[144:147], v[242:245], v[10:13]
	v_mfma_f32_16x16x32_bf16 v[56:59], v[148:151], v[176:179], v[56:59]
	v_mfma_f32_16x16x32_bf16 v[52:55], v[168:171], v[176:179], v[52:55]
	v_mfma_f32_16x16x32_bf16 v[40:43], v[148:151], v[184:187], v[40:43]
	v_mfma_f32_16x16x32_bf16 v[36:39], v[168:171], v[184:187], v[36:39]
	v_mfma_f32_16x16x32_bf16 v[22:25], v[148:151], v[210:213], v[22:25]
	v_mfma_f32_16x16x32_bf16 v[18:21], v[168:171], v[210:213], v[18:21]
	v_mfma_f32_16x16x32_bf16 v[6:9], v[148:151], v[238:241], v[6:9]
	v_mfma_f32_16x16x32_bf16 v[2:5], v[168:171], v[238:241], v[2:5]
	v_mfma_f32_16x16x32_bf16 v[56:59], v[152:155], v[180:183], v[56:59]
	v_mfma_f32_16x16x32_bf16 v[52:55], v[172:175], v[180:183], v[52:55]
	v_mfma_f32_16x16x32_bf16 v[40:43], v[152:155], v[192:195], v[40:43]
	v_mfma_f32_16x16x32_bf16 v[36:39], v[172:175], v[192:195], v[36:39]
	v_mfma_f32_16x16x32_bf16 v[22:25], v[152:155], v[234:237], v[22:25]
	v_mfma_f32_16x16x32_bf16 v[18:21], v[172:175], v[234:237], v[18:21]
	v_mfma_f32_16x16x32_bf16 v[6:9], v[152:155], v[242:245], v[6:9]
	v_mfma_f32_16x16x32_bf16 v[2:5], v[172:175], v[242:245], v[2:5]
	s_add_i32 s49, s49, 2
	s_add_u32 s13, s13, 0x10000
	s_addc_u32 s28, s28, 0
	s_cmp_gt_u32 s49, 61
	s_mov_b64 s[60:61], s[62:63]
	s_barrier
	s_cbranch_scc0 .LBB0_877
	s_and_b64 vcc, exec, s[46:47]
	s_cbranch_vccz .LBB0_880
	s_barrier

.LBB0_1070:
	ds_read_b128 v[100:103], v2 offset:0
	ds_read_b128 v[112:115], v2 offset:1024
	ds_read_b128 v[172:175], v2 offset:2048
	ds_read_b128 v[188:191], v2 offset:3072
	ds_read_b128 v[192:195], v2 offset:16384
	ds_read_b128 v[200:203], v2 offset:17408
	ds_read_b128 v[204:207], v2 offset:18432
	ds_read_b128 v[210:213], v2 offset:19456
	ds_read_b128 v[216:219], v197
	ds_read_b128 v[220:223], v197 offset:1024
	ds_read_b128 v[224:227], v197 offset:2048
	ds_read_b128 v[228:231], v197 offset:3072
	ds_read_b128 v[232:235], v197 offset:4096
	ds_read_b128 v[236:239], v197 offset:5120
	ds_read_b128 v[240:243], v197 offset:6144
	ds_read_b128 v[244:247], v197 offset:7168
	s_add_u32 s34, s12, 0xfff00080
	s_addc_u32 s35, s13, -1
	s_add_i32 s48, 0, 0x10000
	s_cmp_eq_u32 s59, 28
	s_cselect_b32 s67, s61, s35
	s_cselect_b32 s66, s60, s34
	s_cselect_b32 s65, s63, s58
	s_cselect_b32 s64, s62, s28
	s_add_i32 s49, 0, 0x14000
	s_add_i32 m0, s29, 0xc000
	s_nop 0
	global_load_lds_dwordx4 v184, s[12:13]
	s_add_i32 m0, s29, 0xe000
	s_nop 0
	global_load_lds_dwordx4 v186, s[12:13]
	s_waitcnt vmcnt(8) lgkmcnt(0)
	s_barrier
	v_mfma_i32_16x16x64_i8 v[168:171], v[100:103], v[216:219], v[168:171]
	v_mfma_i32_16x16x64_i8 v[160:163], v[172:175], v[216:219], v[160:163]
	v_mfma_i32_16x16x64_i8 v[152:155], v[100:103], v[224:227], v[152:155]
	v_mfma_i32_16x16x64_i8 v[144:147], v[172:175], v[224:227], v[144:147]
	v_mfma_i32_16x16x64_i8 v[136:139], v[100:103], v[232:235], v[136:139]
	v_mfma_i32_16x16x64_i8 v[128:131], v[172:175], v[232:235], v[128:131]
	v_mfma_i32_16x16x64_i8 v[120:123], v[100:103], v[240:243], v[120:123]
	v_mfma_i32_16x16x64_i8 v[108:111], v[172:175], v[240:243], v[108:111]
	v_mfma_i32_16x16x64_i8 v[168:171], v[112:115], v[220:223], v[168:171]
	v_mfma_i32_16x16x64_i8 v[160:163], v[188:191], v[220:223], v[160:163]
	v_mfma_i32_16x16x64_i8 v[152:155], v[112:115], v[228:231], v[152:155]
	v_mfma_i32_16x16x64_i8 v[144:147], v[188:191], v[228:231], v[144:147]
	v_mfma_i32_16x16x64_i8 v[136:139], v[112:115], v[236:239], v[136:139]
	v_mfma_i32_16x16x64_i8 v[128:131], v[188:191], v[236:239], v[128:131]
	v_mfma_i32_16x16x64_i8 v[120:123], v[112:115], v[244:247], v[120:123]
	v_mfma_i32_16x16x64_i8 v[108:111], v[188:191], v[244:247], v[108:111]
	v_mfma_i32_16x16x64_i8 v[164:167], v[192:195], v[216:219], v[164:167]
	v_mfma_i32_16x16x64_i8 v[156:159], v[204:207], v[216:219], v[156:159]
	v_mfma_i32_16x16x64_i8 v[148:151], v[192:195], v[224:227], v[148:151]
	v_mfma_i32_16x16x64_i8 v[140:143], v[204:207], v[224:227], v[140:143]
	v_mfma_i32_16x16x64_i8 v[132:135], v[192:195], v[232:235], v[132:135]
	v_mfma_i32_16x16x64_i8 v[124:127], v[204:207], v[232:235], v[124:127]
	v_mfma_i32_16x16x64_i8 v[116:119], v[192:195], v[240:243], v[116:119]
	v_mfma_i32_16x16x64_i8 v[104:107], v[204:207], v[240:243], v[104:107]
	v_mfma_i32_16x16x64_i8 v[164:167], v[200:203], v[220:223], v[164:167]
	v_mfma_i32_16x16x64_i8 v[156:159], v[210:213], v[220:223], v[156:159]
	v_mfma_i32_16x16x64_i8 v[148:151], v[200:203], v[228:231], v[148:151]
	v_mfma_i32_16x16x64_i8 v[140:143], v[210:213], v[228:231], v[140:143]
	v_mfma_i32_16x16x64_i8 v[132:135], v[200:203], v[236:239], v[132:135]
	v_mfma_i32_16x16x64_i8 v[124:127], v[210:213], v[236:239], v[124:127]
	v_mfma_i32_16x16x64_i8 v[116:119], v[200:203], v[244:247], v[116:119]
	v_mfma_i32_16x16x64_i8 v[104:107], v[210:213], v[244:247], v[104:107]
	s_barrier
	ds_read_b128 v[216:219], v197 offset:16384
	ds_read_b128 v[220:223], v197 offset:17408
	ds_read_b128 v[224:227], v197 offset:18432
	ds_read_b128 v[228:231], v197 offset:19456
	ds_read_b128 v[232:235], v197 offset:20480
	ds_read_b128 v[236:239], v197 offset:21504
	ds_read_b128 v[240:243], v197 offset:22528
	ds_read_b128 v[244:247], v197 offset:23552
	s_add_i32 s34, s48, s0
	s_mov_b32 m0, s34
	s_nop 0
	global_load_lds_dwordx4 v176, s[64:65]
	s_add_i32 m0, s34, 0x2000
	s_add_u32 s34, s64, 0x4000
	s_addc_u32 s35, s65, 0
	s_add_i32 s48, s49, s0
	global_load_lds_dwordx4 v180, s[64:65]
	s_mov_b32 m0, s48
	s_nop 0
	global_load_lds_dwordx4 v176, s[34:35]
	s_add_i32 m0, s48, 0x2000
	s_nop 0
	global_load_lds_dwordx4 v180, s[34:35]
	s_mov_b32 m0, s29
	s_nop 0
	global_load_lds_dwordx4 v178, s[66:67]
	s_mov_b32 m0, s45
	s_nop 0
	global_load_lds_dwordx4 v182, s[66:67]
	s_waitcnt vmcnt(8) lgkmcnt(0)
	s_barrier
	v_mfma_i32_16x16x64_i8 v[96:99], v[100:103], v[216:219], v[96:99]
	v_mfma_i32_16x16x64_i8 v[88:91], v[172:175], v[216:219], v[88:91]
	v_mfma_i32_16x16x64_i8 v[80:83], v[100:103], v[224:227], v[80:83]
	v_mfma_i32_16x16x64_i8 v[72:75], v[172:175], v[224:227], v[72:75]
	v_mfma_i32_16x16x64_i8 v[64:67], v[100:103], v[232:235], v[64:67]
	v_mfma_i32_16x16x64_i8 v[56:59], v[172:175], v[232:235], v[56:59]
	v_mfma_i32_16x16x64_i8 v[48:51], v[100:103], v[240:243], v[48:51]
	v_mfma_i32_16x16x64_i8 v[40:43], v[172:175], v[240:243], v[40:43]
	v_mfma_i32_16x16x64_i8 v[96:99], v[112:115], v[220:223], v[96:99]
	v_mfma_i32_16x16x64_i8 v[88:91], v[188:191], v[220:223], v[88:91]
	v_mfma_i32_16x16x64_i8 v[80:83], v[112:115], v[228:231], v[80:83]
	v_mfma_i32_16x16x64_i8 v[72:75], v[188:191], v[228:231], v[72:75]
	v_mfma_i32_16x16x64_i8 v[64:67], v[112:115], v[236:239], v[64:67]
	v_mfma_i32_16x16x64_i8 v[56:59], v[188:191], v[236:239], v[56:59]
	v_mfma_i32_16x16x64_i8 v[48:51], v[112:115], v[244:247], v[48:51]
	v_mfma_i32_16x16x64_i8 v[40:43], v[188:191], v[244:247], v[40:43]
	v_mfma_i32_16x16x64_i8 v[92:95], v[192:195], v[216:219], v[92:95]
	v_mfma_i32_16x16x64_i8 v[84:87], v[204:207], v[216:219], v[84:87]
	v_mfma_i32_16x16x64_i8 v[76:79], v[192:195], v[224:227], v[76:79]
	v_mfma_i32_16x16x64_i8 v[68:71], v[204:207], v[224:227], v[68:71]
	v_mfma_i32_16x16x64_i8 v[60:63], v[192:195], v[232:235], v[60:63]
	v_mfma_i32_16x16x64_i8 v[52:55], v[204:207], v[232:235], v[52:55]
	v_mfma_i32_16x16x64_i8 v[44:47], v[192:195], v[240:243], v[44:47]
	v_mfma_i32_16x16x64_i8 v[36:39], v[204:207], v[240:243], v[36:39]
	v_mfma_i32_16x16x64_i8 v[92:95], v[200:203], v[220:223], v[92:95]
	v_mfma_i32_16x16x64_i8 v[84:87], v[210:213], v[220:223], v[84:87]
	v_mfma_i32_16x16x64_i8 v[76:79], v[200:203], v[228:231], v[76:79]
	v_mfma_i32_16x16x64_i8 v[68:71], v[210:213], v[228:231], v[68:71]
	v_mfma_i32_16x16x64_i8 v[60:63], v[200:203], v[236:239], v[60:63]
	v_mfma_i32_16x16x64_i8 v[52:55], v[210:213], v[236:239], v[52:55]
	v_mfma_i32_16x16x64_i8 v[44:47], v[200:203], v[244:247], v[44:47]
	v_mfma_i32_16x16x64_i8 v[36:39], v[210:213], v[244:247], v[36:39]
	s_barrier
	ds_read_b128 v[100:103], v2 offset:32768
	ds_read_b128 v[112:115], v2 offset:33792
	ds_read_b128 v[172:175], v2 offset:34816
	ds_read_b128 v[188:191], v2 offset:35840
	ds_read_b128 v[192:195], v2 offset:49152
	ds_read_b128 v[200:203], v2 offset:50176
	ds_read_b128 v[204:207], v2 offset:51200
	ds_read_b128 v[210:213], v2 offset:52224
	ds_read_b128 v[216:219], v197 offset:32768
	ds_read_b128 v[220:223], v197 offset:33792
	ds_read_b128 v[224:227], v197 offset:34816
	ds_read_b128 v[228:231], v197 offset:35840
	ds_read_b128 v[232:235], v197 offset:36864
	ds_read_b128 v[236:239], v197 offset:37888
	ds_read_b128 v[240:243], v197 offset:38912
	ds_read_b128 v[244:247], v197 offset:39936
	s_add_i32 s48, 0, 0x18000
	s_add_i32 s49, 0, 0x1c000
	s_add_u32 s34, s66, 0x100000
	s_addc_u32 s35, s67, 0
	s_mov_b32 m0, s82
	s_nop 0
	global_load_lds_dwordx4 v178, s[34:35]
	s_mov_b32 m0, s90
	s_nop 0
	global_load_lds_dwordx4 v182, s[34:35]
	s_waitcnt vmcnt(8) lgkmcnt(0)
	s_barrier
	v_mfma_i32_16x16x64_i8 v[168:171], v[100:103], v[216:219], v[168:171]
	v_mfma_i32_16x16x64_i8 v[160:163], v[172:175], v[216:219], v[160:163]
	v_mfma_i32_16x16x64_i8 v[152:155], v[100:103], v[224:227], v[152:155]
	v_mfma_i32_16x16x64_i8 v[144:147], v[172:175], v[224:227], v[144:147]
	v_mfma_i32_16x16x64_i8 v[136:139], v[100:103], v[232:235], v[136:139]
	v_mfma_i32_16x16x64_i8 v[128:131], v[172:175], v[232:235], v[128:131]
	v_mfma_i32_16x16x64_i8 v[120:123], v[100:103], v[240:243], v[120:123]
	v_mfma_i32_16x16x64_i8 v[108:111], v[172:175], v[240:243], v[108:111]
	v_mfma_i32_16x16x64_i8 v[168:171], v[112:115], v[220:223], v[168:171]
	v_mfma_i32_16x16x64_i8 v[160:163], v[188:191], v[220:223], v[160:163]
	v_mfma_i32_16x16x64_i8 v[152:155], v[112:115], v[228:231], v[152:155]
	v_mfma_i32_16x16x64_i8 v[144:147], v[188:191], v[228:231], v[144:147]
	v_mfma_i32_16x16x64_i8 v[136:139], v[112:115], v[236:239], v[136:139]
	v_mfma_i32_16x16x64_i8 v[128:131], v[188:191], v[236:239], v[128:131]
	v_mfma_i32_16x16x64_i8 v[120:123], v[112:115], v[244:247], v[120:123]
	v_mfma_i32_16x16x64_i8 v[108:111], v[188:191], v[244:247], v[108:111]
	v_mfma_i32_16x16x64_i8 v[164:167], v[192:195], v[216:219], v[164:167]
	v_mfma_i32_16x16x64_i8 v[156:159], v[204:207], v[216:219], v[156:159]
	v_mfma_i32_16x16x64_i8 v[148:151], v[192:195], v[224:227], v[148:151]
	v_mfma_i32_16x16x64_i8 v[140:143], v[204:207], v[224:227], v[140:143]
	v_mfma_i32_16x16x64_i8 v[132:135], v[192:195], v[232:235], v[132:135]
	v_mfma_i32_16x16x64_i8 v[124:127], v[204:207], v[232:235], v[124:127]
	v_mfma_i32_16x16x64_i8 v[116:119], v[192:195], v[240:243], v[116:119]
	v_mfma_i32_16x16x64_i8 v[104:107], v[204:207], v[240:243], v[104:107]
	v_mfma_i32_16x16x64_i8 v[164:167], v[200:203], v[220:223], v[164:167]
	v_mfma_i32_16x16x64_i8 v[156:159], v[210:213], v[220:223], v[156:159]
	v_mfma_i32_16x16x64_i8 v[148:151], v[200:203], v[228:231], v[148:151]
	v_mfma_i32_16x16x64_i8 v[140:143], v[210:213], v[228:231], v[140:143]
	v_mfma_i32_16x16x64_i8 v[132:135], v[200:203], v[236:239], v[132:135]
	v_mfma_i32_16x16x64_i8 v[124:127], v[210:213], v[236:239], v[124:127]
	v_mfma_i32_16x16x64_i8 v[116:119], v[200:203], v[244:247], v[116:119]
	v_mfma_i32_16x16x64_i8 v[104:107], v[210:213], v[244:247], v[104:107]
	s_barrier
	ds_read_b128 v[216:219], v197 offset:49152
	ds_read_b128 v[220:223], v197 offset:50176
	ds_read_b128 v[224:227], v197 offset:51200
	ds_read_b128 v[228:231], v197 offset:52224
	ds_read_b128 v[232:235], v197 offset:53248
	ds_read_b128 v[236:239], v197 offset:54272
	ds_read_b128 v[240:243], v197 offset:55296
	ds_read_b128 v[244:247], v197 offset:56320
	s_add_u32 s34, s64, 0x8000
	s_addc_u32 s35, s65, 0
	s_add_i32 s48, s48, s0
	s_mov_b32 m0, s48
	s_nop 0
	global_load_lds_dwordx4 v176, s[34:35]
	s_add_i32 m0, s48, 0x2000
	s_mov_b64 s[100:101], s[34:35]
	s_add_u32 s34, s64, 0xc000
	s_addc_u32 s35, s65, 0
	s_add_i32 s48, s49, s0
	global_load_lds_dwordx4 v180, s[100:101]
	s_mov_b32 m0, s48
	s_nop 0
	global_load_lds_dwordx4 v176, s[34:35]
	s_add_i32 m0, s48, 0x2000
	s_nop 0
	global_load_lds_dwordx4 v180, s[34:35]
	s_mov_b32 m0, s91
	s_nop 0
	s_add_u32 s100, s66, s92
	s_addc_u32 s101, s67, s93
	global_load_lds_dwordx4 v178, s[100:101]
	s_mov_b32 m0, s30
	s_nop 0
	s_add_u32 s100, s66, s92
	s_addc_u32 s101, s67, s93
	global_load_lds_dwordx4 v182, s[100:101]
	s_waitcnt vmcnt(8) lgkmcnt(0)
	s_barrier
	v_mfma_i32_16x16x64_i8 v[96:99], v[100:103], v[216:219], v[96:99]
	v_mfma_i32_16x16x64_i8 v[88:91], v[172:175], v[216:219], v[88:91]
	v_mfma_i32_16x16x64_i8 v[80:83], v[100:103], v[224:227], v[80:83]
	v_mfma_i32_16x16x64_i8 v[72:75], v[172:175], v[224:227], v[72:75]
	v_mfma_i32_16x16x64_i8 v[64:67], v[100:103], v[232:235], v[64:67]
	v_mfma_i32_16x16x64_i8 v[56:59], v[172:175], v[232:235], v[56:59]
	v_mfma_i32_16x16x64_i8 v[48:51], v[100:103], v[240:243], v[48:51]
	v_mfma_i32_16x16x64_i8 v[40:43], v[172:175], v[240:243], v[40:43]
	v_mfma_i32_16x16x64_i8 v[96:99], v[112:115], v[220:223], v[96:99]
	v_mfma_i32_16x16x64_i8 v[88:91], v[188:191], v[220:223], v[88:91]
	v_mfma_i32_16x16x64_i8 v[80:83], v[112:115], v[228:231], v[80:83]
	v_mfma_i32_16x16x64_i8 v[72:75], v[188:191], v[228:231], v[72:75]
	v_mfma_i32_16x16x64_i8 v[64:67], v[112:115], v[236:239], v[64:67]
	v_mfma_i32_16x16x64_i8 v[56:59], v[188:191], v[236:239], v[56:59]
	v_mfma_i32_16x16x64_i8 v[48:51], v[112:115], v[244:247], v[48:51]
	v_mfma_i32_16x16x64_i8 v[40:43], v[188:191], v[244:247], v[40:43]
	v_mfma_i32_16x16x64_i8 v[92:95], v[192:195], v[216:219], v[92:95]
	v_mfma_i32_16x16x64_i8 v[84:87], v[204:207], v[216:219], v[84:87]
	v_mfma_i32_16x16x64_i8 v[76:79], v[192:195], v[224:227], v[76:79]
	v_mfma_i32_16x16x64_i8 v[68:71], v[204:207], v[224:227], v[68:71]
	v_mfma_i32_16x16x64_i8 v[60:63], v[192:195], v[232:235], v[60:63]
	v_mfma_i32_16x16x64_i8 v[52:55], v[204:207], v[232:235], v[52:55]
	v_mfma_i32_16x16x64_i8 v[44:47], v[192:195], v[240:243], v[44:47]
	v_mfma_i32_16x16x64_i8 v[36:39], v[204:207], v[240:243], v[36:39]
	v_mfma_i32_16x16x64_i8 v[92:95], v[200:203], v[220:223], v[92:95]
	v_mfma_i32_16x16x64_i8 v[84:87], v[210:213], v[220:223], v[84:87]
	v_mfma_i32_16x16x64_i8 v[76:79], v[200:203], v[228:231], v[76:79]
	v_mfma_i32_16x16x64_i8 v[68:71], v[210:213], v[228:231], v[68:71]
	v_mfma_i32_16x16x64_i8 v[60:63], v[200:203], v[236:239], v[60:63]
	v_mfma_i32_16x16x64_i8 v[52:55], v[210:213], v[236:239], v[52:55]
	v_mfma_i32_16x16x64_i8 v[44:47], v[200:203], v[244:247], v[44:47]
	v_mfma_i32_16x16x64_i8 v[36:39], v[210:213], v[244:247], v[36:39]
	s_add_i32 s59, s59, 2
	s_add_u32 s28, s28, 0x10000
	s_addc_u32 s58, s58, 0
	s_add_u32 s12, s12, 0x100
	s_addc_u32 s13, s13, 0
	s_cmp_gt_u32 s59, 29
	s_barrier
	s_cbranch_scc0 .LBB0_1070
	s_and_b64 vcc, exec, s[46:47]
	s_cbranch_vccz .LBB0_1073
	s_barrier

.LBB0_1261:
	ds_read_b128 v[132:135], v188 offset:0
	ds_read_b128 v[136:139], v188 offset:1024
	ds_read_b128 v[140:143], v188 offset:2048
	ds_read_b128 v[144:147], v188 offset:3072
	ds_read_b128 v[148:151], v188 offset:16384
	ds_read_b128 v[152:155], v188 offset:17408
	ds_read_b128 v[168:171], v188 offset:18432
	ds_read_b128 v[172:175], v188 offset:19456
	ds_read_b128 v[176:179], v187
	ds_read_b128 v[180:183], v187 offset:1024
	ds_read_b128 v[192:195], v187 offset:2048
	ds_read_b128 v[210:213], v187 offset:3072
	ds_read_b128 v[232:235], v187 offset:4096
	ds_read_b128 v[236:239], v187 offset:5120
	ds_read_b128 v[240:243], v187 offset:6144
	ds_read_b128 v[244:247], v187 offset:7168
	s_add_u32 s42, s22, 0x100
	s_addc_u32 s43, s23, 0
	s_add_i32 s34, 0, 0x10000
	s_cmpk_eq_i32 s60, 0xa8
	s_cselect_b32 s51, s19, s43
	s_cselect_b32 s50, s18, s42
	s_cselect_b32 s49, s21, s59
	s_cselect_b32 s48, s20, s58
	s_add_i32 s35, 0, 0x14000
	s_add_i32 m0, s29, 0xc000
	s_nop 0
	global_load_lds_dwordx4 v164, s[22:23]
	s_add_i32 m0, s29, 0xe000
	s_nop 0
	global_load_lds_dwordx4 v166, s[22:23]
	s_waitcnt vmcnt(8) lgkmcnt(0)
	s_barrier
	v_mfma_f32_16x16x32_bf16 v[128:131], v[132:135], v[176:179], v[128:131]
	v_mfma_f32_16x16x32_bf16 v[124:127], v[140:143], v[176:179], v[124:127]
	v_mfma_f32_16x16x32_bf16 v[112:115], v[132:135], v[192:195], v[112:115]
	v_mfma_f32_16x16x32_bf16 v[108:111], v[140:143], v[192:195], v[108:111]
	v_mfma_f32_16x16x32_bf16 v[96:99], v[132:135], v[232:235], v[96:99]
	v_mfma_f32_16x16x32_bf16 v[92:95], v[140:143], v[232:235], v[92:95]
	v_mfma_f32_16x16x32_bf16 v[80:83], v[132:135], v[240:243], v[80:83]
	v_mfma_f32_16x16x32_bf16 v[76:79], v[140:143], v[240:243], v[76:79]
	v_mfma_f32_16x16x32_bf16 v[128:131], v[136:139], v[180:183], v[128:131]
	v_mfma_f32_16x16x32_bf16 v[124:127], v[144:147], v[180:183], v[124:127]
	v_mfma_f32_16x16x32_bf16 v[112:115], v[136:139], v[210:213], v[112:115]
	v_mfma_f32_16x16x32_bf16 v[108:111], v[144:147], v[210:213], v[108:111]
	v_mfma_f32_16x16x32_bf16 v[96:99], v[136:139], v[236:239], v[96:99]
	v_mfma_f32_16x16x32_bf16 v[92:95], v[144:147], v[236:239], v[92:95]
	v_mfma_f32_16x16x32_bf16 v[80:83], v[136:139], v[244:247], v[80:83]
	v_mfma_f32_16x16x32_bf16 v[76:79], v[144:147], v[244:247], v[76:79]
	v_mfma_f32_16x16x32_bf16 v[120:123], v[148:151], v[176:179], v[120:123]
	v_mfma_f32_16x16x32_bf16 v[116:119], v[168:171], v[176:179], v[116:119]
	v_mfma_f32_16x16x32_bf16 v[104:107], v[148:151], v[192:195], v[104:107]
	v_mfma_f32_16x16x32_bf16 v[100:103], v[168:171], v[192:195], v[100:103]
	v_mfma_f32_16x16x32_bf16 v[88:91], v[148:151], v[232:235], v[88:91]
	v_mfma_f32_16x16x32_bf16 v[84:87], v[168:171], v[232:235], v[84:87]
	v_mfma_f32_16x16x32_bf16 v[72:75], v[148:151], v[240:243], v[72:75]
	v_mfma_f32_16x16x32_bf16 v[68:71], v[168:171], v[240:243], v[68:71]
	v_mfma_f32_16x16x32_bf16 v[120:123], v[152:155], v[180:183], v[120:123]
	v_mfma_f32_16x16x32_bf16 v[116:119], v[172:175], v[180:183], v[116:119]
	v_mfma_f32_16x16x32_bf16 v[104:107], v[152:155], v[210:213], v[104:107]
	v_mfma_f32_16x16x32_bf16 v[100:103], v[172:175], v[210:213], v[100:103]
	v_mfma_f32_16x16x32_bf16 v[88:91], v[152:155], v[236:239], v[88:91]
	v_mfma_f32_16x16x32_bf16 v[84:87], v[172:175], v[236:239], v[84:87]
	v_mfma_f32_16x16x32_bf16 v[72:75], v[152:155], v[244:247], v[72:75]
	v_mfma_f32_16x16x32_bf16 v[68:71], v[172:175], v[244:247], v[68:71]
	s_barrier
	ds_read_b128 v[176:179], v187 offset:16384
	ds_read_b128 v[180:183], v187 offset:17408
	ds_read_b128 v[192:195], v187 offset:18432
	ds_read_b128 v[210:213], v187 offset:19456
	ds_read_b128 v[232:235], v187 offset:20480
	ds_read_b128 v[236:239], v187 offset:21504
	ds_read_b128 v[240:243], v187 offset:22528
	ds_read_b128 v[244:247], v187 offset:23552
	s_add_i32 s22, s34, s0
	s_mov_b32 m0, s22
	s_nop 0
	global_load_lds_dwordx4 v156, s[48:49]
	s_add_i32 m0, s22, 0x2000
	s_add_u32 s22, s48, 0x4000
	s_addc_u32 s23, s49, 0
	s_add_i32 s34, s35, s0
	global_load_lds_dwordx4 v160, s[48:49]
	s_mov_b32 m0, s34
	s_nop 0
	global_load_lds_dwordx4 v156, s[22:23]
	s_add_i32 m0, s34, 0x2000
	s_nop 0
	global_load_lds_dwordx4 v160, s[22:23]
	s_mov_b32 m0, s29
	s_nop 0
	global_load_lds_dwordx4 v158, s[50:51]
	s_mov_b32 m0, s45
	s_nop 0
	global_load_lds_dwordx4 v162, s[50:51]
	s_waitcnt vmcnt(8) lgkmcnt(0)
	s_barrier
	v_mfma_f32_16x16x32_bf16 v[64:67], v[132:135], v[176:179], v[64:67]
	v_mfma_f32_16x16x32_bf16 v[60:63], v[140:143], v[176:179], v[60:63]
	v_mfma_f32_16x16x32_bf16 v[48:51], v[132:135], v[192:195], v[48:51]
	v_mfma_f32_16x16x32_bf16 v[44:47], v[140:143], v[192:195], v[44:47]
	v_mfma_f32_16x16x32_bf16 v[30:33], v[132:135], v[232:235], v[30:33]
	v_mfma_f32_16x16x32_bf16 v[26:29], v[140:143], v[232:235], v[26:29]
	v_mfma_f32_16x16x32_bf16 v[14:17], v[132:135], v[240:243], v[14:17]
	v_mfma_f32_16x16x32_bf16 v[10:13], v[140:143], v[240:243], v[10:13]
	v_mfma_f32_16x16x32_bf16 v[64:67], v[136:139], v[180:183], v[64:67]
	v_mfma_f32_16x16x32_bf16 v[60:63], v[144:147], v[180:183], v[60:63]
	v_mfma_f32_16x16x32_bf16 v[48:51], v[136:139], v[210:213], v[48:51]
	v_mfma_f32_16x16x32_bf16 v[44:47], v[144:147], v[210:213], v[44:47]
	v_mfma_f32_16x16x32_bf16 v[30:33], v[136:139], v[236:239], v[30:33]
	v_mfma_f32_16x16x32_bf16 v[26:29], v[144:147], v[236:239], v[26:29]
	v_mfma_f32_16x16x32_bf16 v[14:17], v[136:139], v[244:247], v[14:17]
	v_mfma_f32_16x16x32_bf16 v[10:13], v[144:147], v[244:247], v[10:13]
	v_mfma_f32_16x16x32_bf16 v[56:59], v[148:151], v[176:179], v[56:59]
	v_mfma_f32_16x16x32_bf16 v[52:55], v[168:171], v[176:179], v[52:55]
	v_mfma_f32_16x16x32_bf16 v[40:43], v[148:151], v[192:195], v[40:43]
	v_mfma_f32_16x16x32_bf16 v[36:39], v[168:171], v[192:195], v[36:39]
	v_mfma_f32_16x16x32_bf16 v[22:25], v[148:151], v[232:235], v[22:25]
	v_mfma_f32_16x16x32_bf16 v[18:21], v[168:171], v[232:235], v[18:21]
	v_mfma_f32_16x16x32_bf16 v[6:9], v[148:151], v[240:243], v[6:9]
	v_mfma_f32_16x16x32_bf16 v[2:5], v[168:171], v[240:243], v[2:5]
	v_mfma_f32_16x16x32_bf16 v[56:59], v[152:155], v[180:183], v[56:59]
	v_mfma_f32_16x16x32_bf16 v[52:55], v[172:175], v[180:183], v[52:55]
	v_mfma_f32_16x16x32_bf16 v[40:43], v[152:155], v[210:213], v[40:43]
	v_mfma_f32_16x16x32_bf16 v[36:39], v[172:175], v[210:213], v[36:39]
	v_mfma_f32_16x16x32_bf16 v[22:25], v[152:155], v[236:239], v[22:25]
	v_mfma_f32_16x16x32_bf16 v[18:21], v[172:175], v[236:239], v[18:21]
	v_mfma_f32_16x16x32_bf16 v[6:9], v[152:155], v[244:247], v[6:9]
	v_mfma_f32_16x16x32_bf16 v[2:5], v[172:175], v[244:247], v[2:5]
	s_barrier
	ds_read_b128 v[132:135], v188 offset:32768
	ds_read_b128 v[136:139], v188 offset:33792
	ds_read_b128 v[140:143], v188 offset:34816
	ds_read_b128 v[144:147], v188 offset:35840
	ds_read_b128 v[148:151], v188 offset:49152
	ds_read_b128 v[152:155], v188 offset:50176
	ds_read_b128 v[168:171], v188 offset:51200
	ds_read_b128 v[172:175], v188 offset:52224
	ds_read_b128 v[176:179], v187 offset:32768
	ds_read_b128 v[180:183], v187 offset:33792
	ds_read_b128 v[192:195], v187 offset:34816
	ds_read_b128 v[210:213], v187 offset:35840
	ds_read_b128 v[232:235], v187 offset:36864
	ds_read_b128 v[236:239], v187 offset:37888
	ds_read_b128 v[240:243], v187 offset:38912
	ds_read_b128 v[244:247], v187 offset:39936
	s_add_i32 s34, 0, 0x18000
	s_add_i32 s35, 0, 0x1c000
	s_add_u32 s22, s50, 0x2b0000
	s_addc_u32 s23, s51, 0
	s_mov_b32 m0, s82
	s_nop 0
	global_load_lds_dwordx4 v158, s[22:23]
	s_mov_b32 m0, s90
	s_nop 0
	global_load_lds_dwordx4 v162, s[22:23]
	s_waitcnt vmcnt(8) lgkmcnt(0)
	s_barrier
	v_mfma_f32_16x16x32_bf16 v[128:131], v[132:135], v[176:179], v[128:131]
	v_mfma_f32_16x16x32_bf16 v[124:127], v[140:143], v[176:179], v[124:127]
	v_mfma_f32_16x16x32_bf16 v[112:115], v[132:135], v[192:195], v[112:115]
	v_mfma_f32_16x16x32_bf16 v[108:111], v[140:143], v[192:195], v[108:111]
	v_mfma_f32_16x16x32_bf16 v[96:99], v[132:135], v[232:235], v[96:99]
	v_mfma_f32_16x16x32_bf16 v[92:95], v[140:143], v[232:235], v[92:95]
	v_mfma_f32_16x16x32_bf16 v[80:83], v[132:135], v[240:243], v[80:83]
	v_mfma_f32_16x16x32_bf16 v[76:79], v[140:143], v[240:243], v[76:79]
	v_mfma_f32_16x16x32_bf16 v[128:131], v[136:139], v[180:183], v[128:131]
	v_mfma_f32_16x16x32_bf16 v[124:127], v[144:147], v[180:183], v[124:127]
	v_mfma_f32_16x16x32_bf16 v[112:115], v[136:139], v[210:213], v[112:115]
	v_mfma_f32_16x16x32_bf16 v[108:111], v[144:147], v[210:213], v[108:111]
	v_mfma_f32_16x16x32_bf16 v[96:99], v[136:139], v[236:239], v[96:99]
	v_mfma_f32_16x16x32_bf16 v[92:95], v[144:147], v[236:239], v[92:95]
	v_mfma_f32_16x16x32_bf16 v[80:83], v[136:139], v[244:247], v[80:83]
	v_mfma_f32_16x16x32_bf16 v[76:79], v[144:147], v[244:247], v[76:79]
	v_mfma_f32_16x16x32_bf16 v[120:123], v[148:151], v[176:179], v[120:123]
	v_mfma_f32_16x16x32_bf16 v[116:119], v[168:171], v[176:179], v[116:119]
	v_mfma_f32_16x16x32_bf16 v[104:107], v[148:151], v[192:195], v[104:107]
	v_mfma_f32_16x16x32_bf16 v[100:103], v[168:171], v[192:195], v[100:103]
	v_mfma_f32_16x16x32_bf16 v[88:91], v[148:151], v[232:235], v[88:91]
	v_mfma_f32_16x16x32_bf16 v[84:87], v[168:171], v[232:235], v[84:87]
	v_mfma_f32_16x16x32_bf16 v[72:75], v[148:151], v[240:243], v[72:75]
	v_mfma_f32_16x16x32_bf16 v[68:71], v[168:171], v[240:243], v[68:71]
	v_mfma_f32_16x16x32_bf16 v[120:123], v[152:155], v[180:183], v[120:123]
	v_mfma_f32_16x16x32_bf16 v[116:119], v[172:175], v[180:183], v[116:119]
	v_mfma_f32_16x16x32_bf16 v[104:107], v[152:155], v[210:213], v[104:107]
	v_mfma_f32_16x16x32_bf16 v[100:103], v[172:175], v[210:213], v[100:103]
	v_mfma_f32_16x16x32_bf16 v[88:91], v[152:155], v[236:239], v[88:91]
	v_mfma_f32_16x16x32_bf16 v[84:87], v[172:175], v[236:239], v[84:87]
	v_mfma_f32_16x16x32_bf16 v[72:75], v[152:155], v[244:247], v[72:75]
	v_mfma_f32_16x16x32_bf16 v[68:71], v[172:175], v[244:247], v[68:71]
	s_barrier
	ds_read_b128 v[176:179], v187 offset:49152
	ds_read_b128 v[180:183], v187 offset:50176
	ds_read_b128 v[192:195], v187 offset:51200
	ds_read_b128 v[210:213], v187 offset:52224
	ds_read_b128 v[232:235], v187 offset:53248
	ds_read_b128 v[236:239], v187 offset:54272
	ds_read_b128 v[240:243], v187 offset:55296
	ds_read_b128 v[244:247], v187 offset:56320
	s_add_u32 s22, s48, 0x8000
	s_addc_u32 s23, s49, 0
	s_add_i32 s34, s34, s0
	s_mov_b32 m0, s34
	s_nop 0
	global_load_lds_dwordx4 v156, s[22:23]
	s_add_i32 m0, s34, 0x2000
	s_mov_b64 s[100:101], s[22:23]
	s_add_u32 s22, s48, 0xc000
	s_addc_u32 s23, s49, 0
	s_add_i32 s34, s35, s0
	global_load_lds_dwordx4 v160, s[100:101]
	s_mov_b32 m0, s34
	s_nop 0
	global_load_lds_dwordx4 v156, s[22:23]
	s_add_i32 m0, s34, 0x2000
	s_nop 0
	global_load_lds_dwordx4 v160, s[22:23]
	s_mov_b32 m0, s91
	s_nop 0
	s_add_u32 s100, s50, s92
	s_addc_u32 s101, s51, s93
	global_load_lds_dwordx4 v158, s[100:101]
	s_mov_b32 m0, s30
	s_nop 0
	s_add_u32 s100, s50, s92
	s_addc_u32 s101, s51, s93
	global_load_lds_dwordx4 v162, s[100:101]
	s_waitcnt vmcnt(8) lgkmcnt(0)
	s_barrier
	v_mfma_f32_16x16x32_bf16 v[64:67], v[132:135], v[176:179], v[64:67]
	v_mfma_f32_16x16x32_bf16 v[60:63], v[140:143], v[176:179], v[60:63]
	v_mfma_f32_16x16x32_bf16 v[48:51], v[132:135], v[192:195], v[48:51]
	v_mfma_f32_16x16x32_bf16 v[44:47], v[140:143], v[192:195], v[44:47]
	v_mfma_f32_16x16x32_bf16 v[30:33], v[132:135], v[232:235], v[30:33]
	v_mfma_f32_16x16x32_bf16 v[26:29], v[140:143], v[232:235], v[26:29]
	v_mfma_f32_16x16x32_bf16 v[14:17], v[132:135], v[240:243], v[14:17]
	v_mfma_f32_16x16x32_bf16 v[10:13], v[140:143], v[240:243], v[10:13]
	v_mfma_f32_16x16x32_bf16 v[64:67], v[136:139], v[180:183], v[64:67]
	v_mfma_f32_16x16x32_bf16 v[60:63], v[144:147], v[180:183], v[60:63]
	v_mfma_f32_16x16x32_bf16 v[48:51], v[136:139], v[210:213], v[48:51]
	v_mfma_f32_16x16x32_bf16 v[44:47], v[144:147], v[210:213], v[44:47]
	v_mfma_f32_16x16x32_bf16 v[30:33], v[136:139], v[236:239], v[30:33]
	v_mfma_f32_16x16x32_bf16 v[26:29], v[144:147], v[236:239], v[26:29]
	v_mfma_f32_16x16x32_bf16 v[14:17], v[136:139], v[244:247], v[14:17]
	v_mfma_f32_16x16x32_bf16 v[10:13], v[144:147], v[244:247], v[10:13]
	v_mfma_f32_16x16x32_bf16 v[56:59], v[148:151], v[176:179], v[56:59]
	v_mfma_f32_16x16x32_bf16 v[52:55], v[168:171], v[176:179], v[52:55]
	v_mfma_f32_16x16x32_bf16 v[40:43], v[148:151], v[192:195], v[40:43]
	v_mfma_f32_16x16x32_bf16 v[36:39], v[168:171], v[192:195], v[36:39]
	v_mfma_f32_16x16x32_bf16 v[22:25], v[148:151], v[232:235], v[22:25]
	v_mfma_f32_16x16x32_bf16 v[18:21], v[168:171], v[232:235], v[18:21]
	v_mfma_f32_16x16x32_bf16 v[6:9], v[148:151], v[240:243], v[6:9]
	v_mfma_f32_16x16x32_bf16 v[2:5], v[168:171], v[240:243], v[2:5]
	v_mfma_f32_16x16x32_bf16 v[56:59], v[152:155], v[180:183], v[56:59]
	v_mfma_f32_16x16x32_bf16 v[52:55], v[172:175], v[180:183], v[52:55]
	v_mfma_f32_16x16x32_bf16 v[40:43], v[152:155], v[210:213], v[40:43]
	v_mfma_f32_16x16x32_bf16 v[36:39], v[172:175], v[210:213], v[36:39]
	v_mfma_f32_16x16x32_bf16 v[22:25], v[152:155], v[236:239], v[22:25]
	v_mfma_f32_16x16x32_bf16 v[18:21], v[172:175], v[236:239], v[18:21]
	v_mfma_f32_16x16x32_bf16 v[6:9], v[152:155], v[244:247], v[6:9]
	v_mfma_f32_16x16x32_bf16 v[2:5], v[172:175], v[244:247], v[2:5]
	s_add_i32 s60, s60, 2
	s_add_u32 s58, s58, 0x10000
	s_addc_u32 s59, s59, 0
	s_cmpk_gt_u32 s60, 0xa9
	s_mov_b64 s[22:23], s[42:43]
	s_barrier
	s_cbranch_scc0 .LBB0_1261
	s_and_b64 vcc, exec, s[46:47]
	s_cbranch_vccz .LBB0_1264
	s_barrier
